# plus: norm-gain loads of weight-conversion items issued together (one wait instead of 8-16 dependent round trips)
# baseline (speedup 1.0000x reference)
; #define LAS __attribute__((address_space(3)))
; __device__ __forceinline__ void p0_item(const float* s0, const float* s1, int nv0, int nv1, int N, bf16* dst, int K, LAS float* scr, int lane, const float* gain  ) {
;     const int r = lane >> 4, c4 = lane & 15, hf = c4 >> 3, cc = (c4 & 7) * 4;
;     const float* src = (hf ? s1 : s0) + (size_t)r * N + cc;
;     const bool ok = cc < (hf ? nv1 : nv0);
;     f32x4 v[16];
; #pragma unroll
;     for (int i = 0; i < 16; ++i) v[i] = ok ? __builtin_nontemporal_load((const f32x4*)(src + (size_t)(4 * i) * N)) : (f32x4){0.f, 0.f, 0.f, 0.f};
; #pragma unroll
;     for (int i = 0; i < 16; ++i) { const float gk = gain ? gain[4 * i + r] : 1.f; LAS float* d = scr + (4 * i + r) * 65 + 4 * c4; d[0] = v[i].x * gk; d[1] = v[i].y * gk; d[2] = v[i].z * gk; d[3] = v[i].w * gk; }
; __device__ __forceinline__ void p0_matrix(int type  , const float* W0, const float* W1, int K, int Nsrc, int Ndst, bf16* dst, LAS float* scr, int gw, int NGW, int lane, const float* gain) {
;     const int nruns = Ndst >> 6, nitems = (K >> 6) * nruns;
;     for (int it = gw; it < nitems; it += NGW) {
;         const int kb = it / nruns, nb = it - kb * nruns, n0 = nb * 64, k0 = kb * 64;
;         const float* src = W0; int c0 = n0, c1 = n0 + 32, nv0 = 32, nv1 = 32;
;         if (type == 1) { const int tile = n0 >> 8, r = n0 & 255; src = r < 128 ? W0 : W1; c0 = tile * 128 + (r & 127); c1 = c0 + 32; }
;         else if (type == 2) { c0 = win_src_col(n0, nv0); c1 = win_src_col(n0 + 32, nv1); }
;         const float* rowp = src + (size_t)k0 * Nsrc;
;         p0_item(rowp + c0, rowp + c1, nv0, nv1, Nsrc, dst + (size_t)n0 * K + k0, K, scr, lane, gain ? gain + k0 : nullptr);
.LBB0_15:
	s_mul_hi_i32 s2, s96, 0x2fa0be83
	s_lshr_b32 s3, s2, 31
	s_ashr_i32 s2, s2, 5
	s_add_i32 s2, s2, s3
	s_mul_i32 s3, s2, 0xffffd500
	s_add_i32 s82, s94, s3
	s_lshl_b32 s80, s2, 6
	s_bitcmp0_b32 s96, 1
	s_cselect_b32 s8, s16, s18
	s_cselect_b32 s3, s17, s19
	s_add_u32 s8, s8, s93
	s_mul_i32 s9, s2, 0xffffea80
	s_addc_u32 s3, s3, 0
	s_add_i32 s9, s95, s9
	s_and_b32 s83, s9, 0xffffff80
	s_and_b32 s88, s82, 64
	s_ashr_i32 s81, s80, 31
	s_mul_i32 s2, s2, 0x158000
	s_mul_hi_i32 s9, s80, 0x5600
	s_add_u32 s2, s8, s2
	s_addc_u32 s3, s3, s9
	s_lshl_b64 s[8:9], s[80:81], 2
	s_add_u32 s86, s91, s8
	s_addc_u32 s87, s92, s9
	s_or_b32 s8, s88, s83
	v_or_b32_e32 v2, s8, v131
	v_ashrrev_i32_e32 v3, 31, v2
	v_lshl_add_u64 v[2:3], v[2:3], 2, s[2:3]
	v_lshl_add_u64 v[2:3], v[2:3], 0, v[72:73]
	v_mov_b32_e32 v115, v73
	v_lshl_add_u64 v[2:3], v[2:3], 0, v[114:115]
	v_add_co_u32_e32 v4, vcc, s84, v2
	s_mov_b32 s2, 0x56000
	s_nop 0
	v_addc_co_u32_e32 v5, vcc, 0, v3, vcc
	global_load_dwordx4 v[62:65], v[2:3], off nt
	global_load_dwordx4 v[58:61], v[4:5], off offset:2048 nt
	v_add_co_u32_e32 v4, vcc, s33, v2
	v_cmp_ne_u32_e64 s[8:9], 1, v129
	s_nop 0
	v_addc_co_u32_e32 v5, vcc, 0, v3, vcc
	v_add_co_u32_e32 v6, vcc, s85, v2
	s_nop 1
	v_addc_co_u32_e32 v7, vcc, 0, v3, vcc
	global_load_dwordx4 v[54:57], v[4:5], off nt
	global_load_dwordx4 v[50:53], v[6:7], off offset:2048 nt
	v_add_co_u32_e32 v4, vcc, s2, v2
	s_mov_b32 s2, 0x6b000
	s_nop 0
	v_addc_co_u32_e32 v5, vcc, 0, v3, vcc
	v_add_co_u32_e32 v6, vcc, s2, v2
	s_mov_b32 s2, 0x81000
	s_nop 0
	v_addc_co_u32_e32 v7, vcc, 0, v3, vcc
	global_load_dwordx4 v[46:49], v[4:5], off nt
	global_load_dwordx4 v[42:45], v[6:7], off offset:2048 nt
	v_add_co_u32_e32 v4, vcc, s2, v2
	s_mov_b32 s2, 0x96000
	s_nop 0
	v_addc_co_u32_e32 v5, vcc, 0, v3, vcc
	v_add_co_u32_e32 v6, vcc, s2, v2
	s_mov_b32 s2, 0xac000
	s_nop 0
	v_addc_co_u32_e32 v7, vcc, 0, v3, vcc
	global_load_dwordx4 v[38:41], v[4:5], off nt
	global_load_dwordx4 v[34:37], v[6:7], off offset:2048 nt
	v_add_co_u32_e32 v4, vcc, s2, v2
	s_mov_b32 s2, 0xc1000
	s_nop 0
	v_addc_co_u32_e32 v5, vcc, 0, v3, vcc
	v_add_co_u32_e32 v6, vcc, s2, v2
	s_mov_b32 s2, 0xd7000
	s_nop 0
	v_addc_co_u32_e32 v7, vcc, 0, v3, vcc
	global_load_dwordx4 v[30:33], v[4:5], off nt
	global_load_dwordx4 v[26:29], v[6:7], off offset:2048 nt
	v_add_co_u32_e32 v4, vcc, s2, v2
	s_mov_b32 s2, 0xec000
	s_nop 0
	v_addc_co_u32_e32 v5, vcc, 0, v3, vcc
	v_add_co_u32_e32 v6, vcc, s2, v2
	s_mov_b32 s2, 0x102000
	s_nop 0
	v_addc_co_u32_e32 v7, vcc, 0, v3, vcc
	global_load_dwordx4 v[22:25], v[4:5], off nt
	global_load_dwordx4 v[18:21], v[6:7], off offset:2048 nt
	v_add_co_u32_e32 v4, vcc, s2, v2
	s_nop 1
	v_addc_co_u32_e32 v5, vcc, 0, v3, vcc
	v_add_co_u32_e32 v6, vcc, 0x117000, v2
	s_nop 1
	v_addc_co_u32_e32 v7, vcc, 0, v3, vcc
	global_load_dwordx4 v[14:17], v[4:5], off nt
	global_load_dwordx4 v[10:13], v[6:7], off offset:2048 nt
	v_add_co_u32_e32 v4, vcc, 0x12d000, v2
	s_nop 1
	v_addc_co_u32_e32 v5, vcc, 0, v3, vcc
	v_add_co_u32_e32 v2, vcc, 0x142000, v2
	s_nop 1
	v_addc_co_u32_e32 v3, vcc, 0, v3, vcc
	global_load_dwordx4 v[6:9], v[4:5], off nt
	s_nop 0
	global_load_dwordx4 v[2:5], v[2:3], off offset:2048 nt
	s_andn2_b64 vcc, exec, s[50:51]
	s_cbranch_vccnz .LBB0_38
	v_lshlrev_b32_e32 v81, 2, v70
	v_lshlrev_b32_e32 v156, 2, v70
	global_load_dword v140, v156, s[86:87]
	global_load_dword v141, v156, s[86:87] offset:16
	global_load_dword v142, v156, s[86:87] offset:32
	global_load_dword v143, v156, s[86:87] offset:48
	global_load_dword v144, v156, s[86:87] offset:64
	global_load_dword v145, v156, s[86:87] offset:80
	global_load_dword v146, v156, s[86:87] offset:96
	global_load_dword v147, v156, s[86:87] offset:112
	global_load_dword v148, v156, s[86:87] offset:128
	global_load_dword v149, v156, s[86:87] offset:144
	global_load_dword v150, v156, s[86:87] offset:160
	global_load_dword v151, v156, s[86:87] offset:176
	global_load_dword v152, v156, s[86:87] offset:192
	global_load_dword v153, v156, s[86:87] offset:208
	global_load_dword v154, v156, s[86:87] offset:224
	global_load_dword v155, v156, s[86:87] offset:240
	s_waitcnt vmcnt(0)
	v_mov_b32_e32 v134, v140
	v_mov_b32_e32 v116, v141
	v_add_u32_e32 v81, v67, v130
	s_waitcnt vmcnt(1)
	v_pk_mul_f32 v[136:137], v[62:63], v[134:135] op_sel_hi:[1,0]
	v_pk_mul_f32 v[134:135], v[64:65], v[134:135] op_sel_hi:[1,0]
	ds_write2_b32 v81, v136, v137 offset1:1
	ds_write2_b32 v81, v134, v135 offset0:2 offset1:3
	s_cbranch_execnz .LBB0_18

; #define LAS __attribute__((address_space(3)))
; __device__ __forceinline__ void p0_item(const float* s0, const float* s1, int nv0, int nv1, int N, bf16* dst, int K, LAS float* scr, int lane, const float* gain  ) {
;     ...
;     for (int i = 0; i < 16; ++i) v[i] = ok ? __builtin_nontemporal_load((const f32x4*)(src + (size_t)(4 * i) * N)) : (f32x4){0.f, 0.f, 0.f, 0.f};
; #pragma unroll
;     for (int i = 0; i < 16; ++i) { const float gk = gain ? gain[4 * i + r] : 1.f; LAS float* d = scr + (4 * i + r) * 65 + 4 * c4; d[0] = v[i].x * gk; d[1] = v[i].y * gk; d[2] = v[i].z * gk; d[3] = v[i].w * gk; }
.LBB0_18:
	s_waitcnt vmcnt(0)
	v_pk_mul_f32 v[58:59], v[58:59], v[116:117] op_sel_hi:[1,0]
	v_add_u32_e32 v62, v67, v71
	ds_write2_b32 v62, v58, v59 offset1:1
	v_pk_mul_f32 v[58:59], v[60:61], v[116:117] op_sel_hi:[1,0]
	ds_write2_b32 v62, v58, v59 offset0:2 offset1:3
	s_and_b64 vcc, exec, s[8:9]
	v_add_u32_e32 v59, v67, v113
	s_cbranch_vccnz .LBB0_39
	v_lshlrev_b32_e32 v58, 2, v70
	v_mov_b32_e32 v60, v142
	s_nop 0
	v_mov_b32_e32 v58, v143
	s_waitcnt vmcnt(1)
	v_pk_mul_f32 v[62:63], v[54:55], v[60:61] op_sel_hi:[1,0]
	v_pk_mul_f32 v[60:61], v[56:57], v[60:61] op_sel_hi:[1,0]
	ds_write2_b32 v59, v62, v63 offset1:1
	ds_write2_b32 v59, v60, v61 offset0:2 offset1:3
	s_cbranch_execnz .LBB0_21

; #define LAS __attribute__((address_space(3)))
; __device__ __forceinline__ void p0_item(const float* s0, const float* s1, int nv0, int nv1, int N, bf16* dst, int K, LAS float* scr, int lane, const float* gain  ) {
;     ...
;     for (int i = 0; i < 16; ++i) v[i] = ok ? __builtin_nontemporal_load((const f32x4*)(src + (size_t)(4 * i) * N)) : (f32x4){0.f, 0.f, 0.f, 0.f};
; #pragma unroll
;     for (int i = 0; i < 16; ++i) { const float gk = gain ? gain[4 * i + r] : 1.f; LAS float* d = scr + (4 * i + r) * 65 + 4 * c4; d[0] = v[i].x * gk; d[1] = v[i].y * gk; d[2] = v[i].z * gk; d[3] = v[i].w * gk; }
.LBB0_21:
	s_waitcnt vmcnt(0)
	v_pk_mul_f32 v[50:51], v[50:51], v[58:59] op_sel_hi:[1,0]
	v_add_u32_e32 v54, v67, v118
	ds_write2_b32 v54, v50, v51 offset1:1
	v_pk_mul_f32 v[50:51], v[52:53], v[58:59] op_sel_hi:[1,0]
	ds_write2_b32 v54, v50, v51 offset0:2 offset1:3
	s_and_b64 vcc, exec, s[8:9]
	v_add_u32_e32 v51, v67, v119
	s_cbranch_vccnz .LBB0_40
	v_lshlrev_b32_e32 v50, 2, v70
	v_mov_b32_e32 v52, v144
	s_nop 0
	v_mov_b32_e32 v50, v145
	s_waitcnt vmcnt(1)
	v_pk_mul_f32 v[54:55], v[46:47], v[52:53] op_sel_hi:[1,0]
	v_pk_mul_f32 v[52:53], v[48:49], v[52:53] op_sel_hi:[1,0]
	ds_write2_b32 v51, v54, v55 offset1:1
	ds_write2_b32 v51, v52, v53 offset0:2 offset1:3
	s_cbranch_execnz .LBB0_24

; #define LAS __attribute__((address_space(3)))
; __device__ __forceinline__ void p0_item(const float* s0, const float* s1, int nv0, int nv1, int N, bf16* dst, int K, LAS float* scr, int lane, const float* gain  ) {
;     ...
;     for (int i = 0; i < 16; ++i) v[i] = ok ? __builtin_nontemporal_load((const f32x4*)(src + (size_t)(4 * i) * N)) : (f32x4){0.f, 0.f, 0.f, 0.f};
; #pragma unroll
;     for (int i = 0; i < 16; ++i) { const float gk = gain ? gain[4 * i + r] : 1.f; LAS float* d = scr + (4 * i + r) * 65 + 4 * c4; d[0] = v[i].x * gk; d[1] = v[i].y * gk; d[2] = v[i].z * gk; d[3] = v[i].w * gk; }
.LBB0_24:
	s_waitcnt vmcnt(0)
	v_pk_mul_f32 v[42:43], v[42:43], v[50:51] op_sel_hi:[1,0]
	v_add_u32_e32 v46, v67, v120
	ds_write2_b32 v46, v42, v43 offset1:1
	v_pk_mul_f32 v[42:43], v[44:45], v[50:51] op_sel_hi:[1,0]
	ds_write2_b32 v46, v42, v43 offset0:2 offset1:3
	s_and_b64 vcc, exec, s[8:9]
	v_add_u32_e32 v43, v67, v121
	s_cbranch_vccnz .LBB0_41
	v_lshlrev_b32_e32 v42, 2, v70
	v_mov_b32_e32 v44, v146
	s_nop 0
	v_mov_b32_e32 v42, v147
	s_waitcnt vmcnt(1)
	v_pk_mul_f32 v[46:47], v[38:39], v[44:45] op_sel_hi:[1,0]
	v_pk_mul_f32 v[44:45], v[40:41], v[44:45] op_sel_hi:[1,0]
	ds_write2_b32 v43, v46, v47 offset1:1
	ds_write2_b32 v43, v44, v45 offset0:2 offset1:3
	s_cbranch_execnz .LBB0_27

; #define LAS __attribute__((address_space(3)))
; __device__ __forceinline__ void p0_item(const float* s0, const float* s1, int nv0, int nv1, int N, bf16* dst, int K, LAS float* scr, int lane, const float* gain  ) {
;     ...
;     for (int i = 0; i < 16; ++i) v[i] = ok ? __builtin_nontemporal_load((const f32x4*)(src + (size_t)(4 * i) * N)) : (f32x4){0.f, 0.f, 0.f, 0.f};
; #pragma unroll
;     for (int i = 0; i < 16; ++i) { const float gk = gain ? gain[4 * i + r] : 1.f; LAS float* d = scr + (4 * i + r) * 65 + 4 * c4; d[0] = v[i].x * gk; d[1] = v[i].y * gk; d[2] = v[i].z * gk; d[3] = v[i].w * gk; }
.LBB0_27:
	s_waitcnt vmcnt(0)
	v_pk_mul_f32 v[34:35], v[34:35], v[42:43] op_sel_hi:[1,0]
	v_add_u32_e32 v38, v67, v122
	ds_write2_b32 v38, v34, v35 offset1:1
	v_pk_mul_f32 v[34:35], v[36:37], v[42:43] op_sel_hi:[1,0]
	ds_write2_b32 v38, v34, v35 offset0:2 offset1:3
	s_and_b64 vcc, exec, s[8:9]
	v_add_u32_e32 v35, v67, v123
	s_cbranch_vccnz .LBB0_42
	v_lshlrev_b32_e32 v34, 2, v70
	v_mov_b32_e32 v36, v148
	s_nop 0
	v_mov_b32_e32 v34, v149
	s_waitcnt vmcnt(1)
	v_pk_mul_f32 v[38:39], v[30:31], v[36:37] op_sel_hi:[1,0]
	v_pk_mul_f32 v[36:37], v[32:33], v[36:37] op_sel_hi:[1,0]
	ds_write2_b32 v35, v38, v39 offset1:1
	ds_write2_b32 v35, v36, v37 offset0:2 offset1:3
	s_cbranch_execnz .LBB0_30

; #define LAS __attribute__((address_space(3)))
; __device__ __forceinline__ void p0_item(const float* s0, const float* s1, int nv0, int nv1, int N, bf16* dst, int K, LAS float* scr, int lane, const float* gain  ) {
;     ...
;     for (int i = 0; i < 16; ++i) v[i] = ok ? __builtin_nontemporal_load((const f32x4*)(src + (size_t)(4 * i) * N)) : (f32x4){0.f, 0.f, 0.f, 0.f};
; #pragma unroll
;     for (int i = 0; i < 16; ++i) { const float gk = gain ? gain[4 * i + r] : 1.f; LAS float* d = scr + (4 * i + r) * 65 + 4 * c4; d[0] = v[i].x * gk; d[1] = v[i].y * gk; d[2] = v[i].z * gk; d[3] = v[i].w * gk; }
.LBB0_30:
	s_waitcnt vmcnt(0)
	v_pk_mul_f32 v[26:27], v[26:27], v[34:35] op_sel_hi:[1,0]
	v_add_u32_e32 v30, v67, v124
	ds_write2_b32 v30, v26, v27 offset1:1
	v_pk_mul_f32 v[26:27], v[28:29], v[34:35] op_sel_hi:[1,0]
	ds_write2_b32 v30, v26, v27 offset0:2 offset1:3
	s_and_b64 vcc, exec, s[8:9]
	v_add_u32_e32 v27, v67, v125
	s_cbranch_vccnz .LBB0_43
	v_lshlrev_b32_e32 v26, 2, v70
	v_mov_b32_e32 v28, v150
	s_nop 0
	v_mov_b32_e32 v26, v151
	s_waitcnt vmcnt(1)
	v_pk_mul_f32 v[30:31], v[22:23], v[28:29] op_sel_hi:[1,0]
	v_pk_mul_f32 v[28:29], v[24:25], v[28:29] op_sel_hi:[1,0]
	ds_write2_b32 v27, v30, v31 offset1:1
	ds_write2_b32 v27, v28, v29 offset0:2 offset1:3
	s_cbranch_execnz .LBB0_33

; #define LAS __attribute__((address_space(3)))
; __device__ __forceinline__ void p0_item(const float* s0, const float* s1, int nv0, int nv1, int N, bf16* dst, int K, LAS float* scr, int lane, const float* gain  ) {
;     ...
;     for (int i = 0; i < 16; ++i) v[i] = ok ? __builtin_nontemporal_load((const f32x4*)(src + (size_t)(4 * i) * N)) : (f32x4){0.f, 0.f, 0.f, 0.f};
; #pragma unroll
;     for (int i = 0; i < 16; ++i) { const float gk = gain ? gain[4 * i + r] : 1.f; LAS float* d = scr + (4 * i + r) * 65 + 4 * c4; d[0] = v[i].x * gk; d[1] = v[i].y * gk; d[2] = v[i].z * gk; d[3] = v[i].w * gk; }
.LBB0_33:
	s_waitcnt vmcnt(0)
	v_pk_mul_f32 v[18:19], v[18:19], v[26:27] op_sel_hi:[1,0]
	v_add_u32_e32 v22, 0x410, v27
	ds_write2_b32 v22, v18, v19 offset1:1
	v_pk_mul_f32 v[18:19], v[20:21], v[26:27] op_sel_hi:[1,0]
	v_add_u32_e32 v20, 0x418, v27
	ds_write2_b32 v20, v18, v19 offset1:1
	s_and_b64 vcc, exec, s[8:9]
	v_add_u32_e32 v19, 0x820, v27
	v_add_u32_e32 v20, 0x828, v27
	s_cbranch_vccnz .LBB0_44
	v_lshlrev_b32_e32 v18, 2, v70
	v_mov_b32_e32 v22, v152
	s_nop 0
	v_mov_b32_e32 v18, v153
	s_waitcnt vmcnt(1)
	v_pk_mul_f32 v[24:25], v[14:15], v[22:23] op_sel_hi:[1,0]
	v_pk_mul_f32 v[22:23], v[16:17], v[22:23] op_sel_hi:[1,0]
	ds_write2_b32 v19, v24, v25 offset1:1
	ds_write2_b32 v20, v22, v23 offset1:1
	s_cbranch_execnz .LBB0_36

; #define LAS __attribute__((address_space(3)))
; __device__ __forceinline__ void p0_item(const float* s0, const float* s1, int nv0, int nv1, int N, bf16* dst, int K, LAS float* scr, int lane, const float* gain  ) {
;     ...
;     for (int i = 0; i < 16; ++i) v[i] = ok ? __builtin_nontemporal_load((const f32x4*)(src + (size_t)(4 * i) * N)) : (f32x4){0.f, 0.f, 0.f, 0.f};
; #pragma unroll
;     for (int i = 0; i < 16; ++i) { const float gk = gain ? gain[4 * i + r] : 1.f; LAS float* d = scr + (4 * i + r) * 65 + 4 * c4; d[0] = v[i].x * gk; d[1] = v[i].y * gk; d[2] = v[i].z * gk; d[3] = v[i].w * gk; }
.LBB0_36:
	s_waitcnt vmcnt(0)
	v_pk_mul_f32 v[10:11], v[10:11], v[18:19] op_sel_hi:[1,0]
	v_add_u32_e32 v14, 0xc30, v27
	ds_write2_b32 v14, v10, v11 offset1:1
	v_pk_mul_f32 v[10:11], v[12:13], v[18:19] op_sel_hi:[1,0]
	v_add_u32_e32 v12, 0xc38, v27
	ds_write2_b32 v12, v10, v11 offset1:1
	s_and_b64 vcc, exec, s[8:9]
	v_add_u32_e32 v11, 0x1040, v27
	v_add_u32_e32 v12, 0x1048, v27
	s_cbranch_vccnz .LBB0_45
	v_lshlrev_b32_e32 v10, 2, v70
	v_mov_b32_e32 v14, v154
	s_nop 0
	v_mov_b32_e32 v10, v155
	s_waitcnt vmcnt(1)
	v_pk_mul_f32 v[16:17], v[6:7], v[14:15] op_sel_hi:[1,0]
	v_pk_mul_f32 v[14:15], v[8:9], v[14:15] op_sel_hi:[1,0]
	ds_write2_b32 v11, v16, v17 offset1:1
	ds_write2_b32 v12, v14, v15 offset1:1
	s_cbranch_execnz .LBB0_14
	s_branch .LBB0_46

; #define LAS __attribute__((address_space(3)))
; __device__ __forceinline__ void p0_item(const float* s0, const float* s1, int nv0, int nv1, int N, bf16* dst, int K, LAS float* scr, int lane, const float* gain  ) {
;     const int r = lane >> 4, c4 = lane & 15, hf = c4 >> 3, cc = (c4 & 7) * 4;
;     const float* src = (hf ? s1 : s0) + (size_t)r * N + cc;
;     const bool ok = cc < (hf ? nv1 : nv0);
;     f32x4 v[16];
; #pragma unroll
;     for (int i = 0; i < 16; ++i) v[i] = ok ? __builtin_nontemporal_load((const f32x4*)(src + (size_t)(4 * i) * N)) : (f32x4){0.f, 0.f, 0.f, 0.f};
; #pragma unroll
;     for (int i = 0; i < 16; ++i) { const float gk = gain ? gain[4 * i + r] : 1.f; LAS float* d = scr + (4 * i + r) * 65 + 4 * c4; d[0] = v[i].x * gk; d[1] = v[i].y * gk; d[2] = v[i].z * gk; d[3] = v[i].w * gk; }
.LBB0_118:
	s_or_b64 exec, exec, s[86:87]
	s_ashr_i32 s83, s82, 31
	s_lshl_b64 s[2:3], s[82:83], 2
	s_add_u32 s86, s22, s2
	v_cndmask_b32_e64 v81, 0, 1, s[54:55]
	s_addc_u32 s87, s23, s3
	v_cmp_ne_u32_e64 s[8:9], 1, v81
	s_andn2_b64 vcc, exec, s[54:55]
	v_add_u32_e32 v83, v128, v130
	v_lshlrev_b32_e32 v81, 2, v70
	s_cbranch_vccnz .LBB0_141
	v_lshlrev_b32_e32 v156, 2, v70
	global_load_dword v140, v156, s[86:87]
	global_load_dword v141, v156, s[86:87] offset:16
	global_load_dword v142, v156, s[86:87] offset:32
	global_load_dword v143, v156, s[86:87] offset:48
	global_load_dword v144, v156, s[86:87] offset:64
	global_load_dword v145, v156, s[86:87] offset:80
	global_load_dword v146, v156, s[86:87] offset:96
	global_load_dword v147, v156, s[86:87] offset:112
	global_load_dword v148, v156, s[86:87] offset:128
	global_load_dword v149, v156, s[86:87] offset:144
	global_load_dword v150, v156, s[86:87] offset:160
	global_load_dword v151, v156, s[86:87] offset:176
	global_load_dword v152, v156, s[86:87] offset:192
	global_load_dword v153, v156, s[86:87] offset:208
	global_load_dword v154, v156, s[86:87] offset:224
	global_load_dword v155, v156, s[86:87] offset:240
	s_waitcnt vmcnt(0)
	v_mov_b32_e32 v134, v140
	v_mov_b32_e32 v116, v141
	s_waitcnt vmcnt(1)
	v_pk_mul_f32 v[136:137], v[10:11], v[134:135] op_sel_hi:[1,0]
	v_pk_mul_f32 v[134:135], v[12:13], v[134:135] op_sel_hi:[1,0]
	ds_write2_b32 v83, v136, v137 offset1:1
	ds_write2_b32 v83, v134, v135 offset0:2 offset1:3
	s_cbranch_execnz .LBB0_121

; #define LAS __attribute__((address_space(3)))
; __device__ __forceinline__ void p0_item(const float* s0, const float* s1, int nv0, int nv1, int N, bf16* dst, int K, LAS float* scr, int lane, const float* gain  ) {
;     ...
;     for (int i = 0; i < 16; ++i) v[i] = ok ? __builtin_nontemporal_load((const f32x4*)(src + (size_t)(4 * i) * N)) : (f32x4){0.f, 0.f, 0.f, 0.f};
; #pragma unroll
;     for (int i = 0; i < 16; ++i) { const float gk = gain ? gain[4 * i + r] : 1.f; LAS float* d = scr + (4 * i + r) * 65 + 4 * c4; d[0] = v[i].x * gk; d[1] = v[i].y * gk; d[2] = v[i].z * gk; d[3] = v[i].w * gk; }
.LBB0_121:
	s_waitcnt vmcnt(0)
	v_pk_mul_f32 v[2:3], v[2:3], v[116:117] op_sel_hi:[1,0]
	v_add_u32_e32 v10, v128, v71
	ds_write2_b32 v10, v2, v3 offset1:1
	v_pk_mul_f32 v[2:3], v[4:5], v[116:117] op_sel_hi:[1,0]
	ds_write2_b32 v10, v2, v3 offset0:2 offset1:3
	s_and_b64 vcc, exec, s[8:9]
	v_add_u32_e32 v3, v128, v113
	s_cbranch_vccnz .LBB0_142
	v_mov_b32_e32 v4, v142
	v_mov_b32_e32 v2, v143
	s_waitcnt vmcnt(1)
	v_pk_mul_f32 v[10:11], v[18:19], v[4:5] op_sel_hi:[1,0]
	v_pk_mul_f32 v[4:5], v[20:21], v[4:5] op_sel_hi:[1,0]
	ds_write2_b32 v3, v10, v11 offset1:1
	ds_write2_b32 v3, v4, v5 offset0:2 offset1:3
	s_cbranch_execnz .LBB0_124

; #define LAS __attribute__((address_space(3)))
; __device__ __forceinline__ void p0_item(const float* s0, const float* s1, int nv0, int nv1, int N, bf16* dst, int K, LAS float* scr, int lane, const float* gain  ) {
;     ...
;     for (int i = 0; i < 16; ++i) v[i] = ok ? __builtin_nontemporal_load((const f32x4*)(src + (size_t)(4 * i) * N)) : (f32x4){0.f, 0.f, 0.f, 0.f};
; #pragma unroll
;     for (int i = 0; i < 16; ++i) { const float gk = gain ? gain[4 * i + r] : 1.f; LAS float* d = scr + (4 * i + r) * 65 + 4 * c4; d[0] = v[i].x * gk; d[1] = v[i].y * gk; d[2] = v[i].z * gk; d[3] = v[i].w * gk; }
.LBB0_124:
	s_waitcnt vmcnt(0)
	v_pk_mul_f32 v[4:5], v[6:7], v[2:3] op_sel_hi:[1,0]
	v_add_u32_e32 v6, v128, v118
	v_pk_mul_f32 v[2:3], v[8:9], v[2:3] op_sel_hi:[1,0]
	ds_write2_b32 v6, v2, v3 offset0:2 offset1:3
	s_and_b64 vcc, exec, s[8:9]
	v_add_u32_e32 v3, v128, v119
	ds_write2_b32 v6, v4, v5 offset1:1
	s_cbranch_vccnz .LBB0_143
	v_mov_b32_e32 v4, v144
	v_mov_b32_e32 v2, v145
	s_waitcnt vmcnt(1)
	v_pk_mul_f32 v[6:7], v[26:27], v[4:5] op_sel_hi:[1,0]
	v_pk_mul_f32 v[4:5], v[28:29], v[4:5] op_sel_hi:[1,0]
	ds_write2_b32 v3, v6, v7 offset1:1
	ds_write2_b32 v3, v4, v5 offset0:2 offset1:3
	s_cbranch_execnz .LBB0_127

; #define LAS __attribute__((address_space(3)))
; __device__ __forceinline__ void p0_item(const float* s0, const float* s1, int nv0, int nv1, int N, bf16* dst, int K, LAS float* scr, int lane, const float* gain  ) {
;     ...
;     for (int i = 0; i < 16; ++i) v[i] = ok ? __builtin_nontemporal_load((const f32x4*)(src + (size_t)(4 * i) * N)) : (f32x4){0.f, 0.f, 0.f, 0.f};
; #pragma unroll
;     for (int i = 0; i < 16; ++i) { const float gk = gain ? gain[4 * i + r] : 1.f; LAS float* d = scr + (4 * i + r) * 65 + 4 * c4; d[0] = v[i].x * gk; d[1] = v[i].y * gk; d[2] = v[i].z * gk; d[3] = v[i].w * gk; }
.LBB0_127:
	s_waitcnt vmcnt(0)
	v_pk_mul_f32 v[4:5], v[14:15], v[2:3] op_sel_hi:[1,0]
	v_add_u32_e32 v6, v128, v120
	v_pk_mul_f32 v[2:3], v[16:17], v[2:3] op_sel_hi:[1,0]
	ds_write2_b32 v6, v2, v3 offset0:2 offset1:3
	s_and_b64 vcc, exec, s[8:9]
	v_add_u32_e32 v3, v128, v121
	ds_write2_b32 v6, v4, v5 offset1:1
	s_cbranch_vccnz .LBB0_144
	v_mov_b32_e32 v4, v146
	v_mov_b32_e32 v2, v147
	s_waitcnt vmcnt(1)
	v_pk_mul_f32 v[6:7], v[34:35], v[4:5] op_sel_hi:[1,0]
	v_pk_mul_f32 v[4:5], v[36:37], v[4:5] op_sel_hi:[1,0]
	ds_write2_b32 v3, v6, v7 offset1:1
	ds_write2_b32 v3, v4, v5 offset0:2 offset1:3
	s_cbranch_execnz .LBB0_130

; #define LAS __attribute__((address_space(3)))
; __device__ __forceinline__ void p0_item(const float* s0, const float* s1, int nv0, int nv1, int N, bf16* dst, int K, LAS float* scr, int lane, const float* gain  ) {
;     ...
;     for (int i = 0; i < 16; ++i) v[i] = ok ? __builtin_nontemporal_load((const f32x4*)(src + (size_t)(4 * i) * N)) : (f32x4){0.f, 0.f, 0.f, 0.f};
; #pragma unroll
;     for (int i = 0; i < 16; ++i) { const float gk = gain ? gain[4 * i + r] : 1.f; LAS float* d = scr + (4 * i + r) * 65 + 4 * c4; d[0] = v[i].x * gk; d[1] = v[i].y * gk; d[2] = v[i].z * gk; d[3] = v[i].w * gk; }
.LBB0_130:
	s_waitcnt vmcnt(0)
	v_pk_mul_f32 v[4:5], v[22:23], v[2:3] op_sel_hi:[1,0]
	v_add_u32_e32 v6, v128, v122
	v_pk_mul_f32 v[2:3], v[24:25], v[2:3] op_sel_hi:[1,0]
	ds_write2_b32 v6, v2, v3 offset0:2 offset1:3
	s_and_b64 vcc, exec, s[8:9]
	v_add_u32_e32 v3, v128, v123
	ds_write2_b32 v6, v4, v5 offset1:1
	s_cbranch_vccnz .LBB0_145
	v_mov_b32_e32 v4, v148
	v_mov_b32_e32 v2, v149
	s_waitcnt vmcnt(1)
	v_pk_mul_f32 v[6:7], v[42:43], v[4:5] op_sel_hi:[1,0]
	v_pk_mul_f32 v[4:5], v[44:45], v[4:5] op_sel_hi:[1,0]
	ds_write2_b32 v3, v6, v7 offset1:1
	ds_write2_b32 v3, v4, v5 offset0:2 offset1:3
	s_cbranch_execnz .LBB0_133

; #define LAS __attribute__((address_space(3)))
; __device__ __forceinline__ void p0_item(const float* s0, const float* s1, int nv0, int nv1, int N, bf16* dst, int K, LAS float* scr, int lane, const float* gain  ) {
;     ...
;     for (int i = 0; i < 16; ++i) v[i] = ok ? __builtin_nontemporal_load((const f32x4*)(src + (size_t)(4 * i) * N)) : (f32x4){0.f, 0.f, 0.f, 0.f};
; #pragma unroll
;     for (int i = 0; i < 16; ++i) { const float gk = gain ? gain[4 * i + r] : 1.f; LAS float* d = scr + (4 * i + r) * 65 + 4 * c4; d[0] = v[i].x * gk; d[1] = v[i].y * gk; d[2] = v[i].z * gk; d[3] = v[i].w * gk; }
.LBB0_133:
	s_waitcnt vmcnt(0)
	v_pk_mul_f32 v[4:5], v[30:31], v[2:3] op_sel_hi:[1,0]
	v_add_u32_e32 v6, v128, v124
	v_pk_mul_f32 v[2:3], v[32:33], v[2:3] op_sel_hi:[1,0]
	ds_write2_b32 v6, v2, v3 offset0:2 offset1:3
	s_and_b64 vcc, exec, s[8:9]
	v_add_u32_e32 v3, v128, v125
	ds_write2_b32 v6, v4, v5 offset1:1
	s_cbranch_vccnz .LBB0_146
	v_mov_b32_e32 v4, v150
	v_mov_b32_e32 v2, v151
	s_waitcnt vmcnt(1)
	v_pk_mul_f32 v[6:7], v[50:51], v[4:5] op_sel_hi:[1,0]
	v_pk_mul_f32 v[4:5], v[52:53], v[4:5] op_sel_hi:[1,0]
	ds_write2_b32 v3, v6, v7 offset1:1
	ds_write2_b32 v3, v4, v5 offset0:2 offset1:3
	s_cbranch_execnz .LBB0_136

; #define LAS __attribute__((address_space(3)))
; __device__ __forceinline__ void p0_item(const float* s0, const float* s1, int nv0, int nv1, int N, bf16* dst, int K, LAS float* scr, int lane, const float* gain  ) {
;     ...
;     for (int i = 0; i < 16; ++i) v[i] = ok ? __builtin_nontemporal_load((const f32x4*)(src + (size_t)(4 * i) * N)) : (f32x4){0.f, 0.f, 0.f, 0.f};
; #pragma unroll
;     for (int i = 0; i < 16; ++i) { const float gk = gain ? gain[4 * i + r] : 1.f; LAS float* d = scr + (4 * i + r) * 65 + 4 * c4; d[0] = v[i].x * gk; d[1] = v[i].y * gk; d[2] = v[i].z * gk; d[3] = v[i].w * gk; }
.LBB0_136:
	s_waitcnt vmcnt(0)
	v_pk_mul_f32 v[4:5], v[38:39], v[2:3] op_sel_hi:[1,0]
	v_add_u32_e32 v6, 0x410, v3
	ds_write2_b32 v6, v4, v5 offset1:1
	v_pk_mul_f32 v[4:5], v[40:41], v[2:3] op_sel_hi:[1,0]
	v_add_u32_e32 v2, 0x418, v3
	ds_write2_b32 v2, v4, v5 offset1:1
	s_and_b64 vcc, exec, s[8:9]
	v_add_u32_e32 v4, 0x820, v3
	v_add_u32_e32 v5, 0x828, v3
	s_cbranch_vccnz .LBB0_147
	v_mov_b32_e32 v6, v152
	v_mov_b32_e32 v2, v153
	s_waitcnt vmcnt(1)
	v_pk_mul_f32 v[8:9], v[58:59], v[6:7] op_sel_hi:[1,0]
	v_pk_mul_f32 v[6:7], v[60:61], v[6:7] op_sel_hi:[1,0]
	ds_write2_b32 v4, v8, v9 offset1:1
	ds_write2_b32 v5, v6, v7 offset1:1
	s_cbranch_execnz .LBB0_139

; #define LAS __attribute__((address_space(3)))
; __device__ __forceinline__ void p0_item(const float* s0, const float* s1, int nv0, int nv1, int N, bf16* dst, int K, LAS float* scr, int lane, const float* gain  ) {
;     ...
;     for (int i = 0; i < 16; ++i) v[i] = ok ? __builtin_nontemporal_load((const f32x4*)(src + (size_t)(4 * i) * N)) : (f32x4){0.f, 0.f, 0.f, 0.f};
; #pragma unroll
;     for (int i = 0; i < 16; ++i) { const float gk = gain ? gain[4 * i + r] : 1.f; LAS float* d = scr + (4 * i + r) * 65 + 4 * c4; d[0] = v[i].x * gk; d[1] = v[i].y * gk; d[2] = v[i].z * gk; d[3] = v[i].w * gk; }
.LBB0_139:
	s_waitcnt vmcnt(0)
	v_pk_mul_f32 v[4:5], v[46:47], v[2:3] op_sel_hi:[1,0]
	v_add_u32_e32 v6, 0xc30, v3
	ds_write2_b32 v6, v4, v5 offset1:1
	v_pk_mul_f32 v[4:5], v[48:49], v[2:3] op_sel_hi:[1,0]
	v_add_u32_e32 v2, 0xc38, v3
	ds_write2_b32 v2, v4, v5 offset1:1
	s_and_b64 vcc, exec, s[8:9]
	v_add_u32_e32 v4, 0x1040, v3
	v_add_u32_e32 v5, 0x1048, v3
	s_cbranch_vccnz .LBB0_148
	v_mov_b32_e32 v6, v154
	v_mov_b32_e32 v2, v155
	s_waitcnt vmcnt(1)
	v_pk_mul_f32 v[8:9], v[62:63], v[6:7] op_sel_hi:[1,0]
	v_pk_mul_f32 v[6:7], v[64:65], v[6:7] op_sel_hi:[1,0]
	ds_write2_b32 v4, v8, v9 offset1:1
	ds_write2_b32 v5, v6, v7 offset1:1
	s_cbranch_execnz .LBB0_53
	s_branch .LBB0_149

; #define LAS __attribute__((address_space(3)))
; __device__ __forceinline__ void p0_item(const float* s0, const float* s1, int nv0, int nv1, int N, bf16* dst, int K, LAS float* scr, int lane, const float* gain  ) {
;     const int r = lane >> 4, c4 = lane & 15, hf = c4 >> 3, cc = (c4 & 7) * 4;
;     const float* src = (hf ? s1 : s0) + (size_t)r * N + cc;
;     const bool ok = cc < (hf ? nv1 : nv0);
;     f32x4 v[16];
; #pragma unroll
;     for (int i = 0; i < 16; ++i) v[i] = ok ? __builtin_nontemporal_load((const f32x4*)(src + (size_t)(4 * i) * N)) : (f32x4){0.f, 0.f, 0.f, 0.f};
; #pragma unroll
;     for (int i = 0; i < 16; ++i) { const float gk = gain ? gain[4 * i + r] : 1.f; LAS float* d = scr + (4 * i + r) * 65 + 4 * c4; d[0] = v[i].x * gk; d[1] = v[i].y * gk; d[2] = v[i].z * gk; d[3] = v[i].w * gk; }
; __device__ __forceinline__ void p0_matrix(int type  , const float* W0, const float* W1, int K, int Nsrc, int Ndst, bf16* dst, LAS float* scr, int gw, int NGW, int lane, const float* gain) {
;     const int nruns = Ndst >> 6, nitems = (K >> 6) * nruns;
;     for (int it = gw; it < nitems; it += NGW) {
;         const int kb = it / nruns, nb = it - kb * nruns, n0 = nb * 64, k0 = kb * 64;
;         const float* src = W0; int c0 = n0, c1 = n0 + 32, nv0 = 32, nv1 = 32;
;         if (type == 1) { const int tile = n0 >> 8, r = n0 & 255; src = r < 128 ? W0 : W1; c0 = tile * 128 + (r & 127); c1 = c0 + 32; }
;         else if (type == 2) { c0 = win_src_col(n0, nv0); c1 = win_src_col(n0 + 32, nv1); }
;         const float* rowp = src + (size_t)k0 * Nsrc;
;         p0_item(rowp + c0, rowp + c1, nv0, nv1, Nsrc, dst + (size_t)n0 * K + k0, K, scr, lane, gain ? gain + k0 : nullptr);
.LBB0_1418:
	s_mul_hi_i32 s0, s26, 0x2fa0be83
	s_lshr_b32 s1, s0, 31
	s_ashr_i32 s0, s0, 5
	s_add_i32 s0, s0, s1
	s_mul_i32 s1, s0, 0xffffd500
	s_add_i32 s10, s24, s1
	s_lshl_b32 s6, s0, 6
	v_readlane_b32 s12, v253, 26
	s_bitcmp0_b32 s26, 1
	v_readlane_b32 s14, v253, 28
	v_readlane_b32 s15, v253, 29
	s_cselect_b32 s7, s14, s34
	s_mul_i32 s11, s20, 0x2b00000
	s_cselect_b32 s1, s15, s35
	s_add_u32 s11, s7, s11
	s_mul_i32 s7, s0, 0xffffea80
	s_addc_u32 s1, s1, 0
	s_add_i32 s7, s17, s7
	v_readlane_b32 s13, v253, 27
	s_and_b32 s12, s7, 0xffffff80
	s_ashr_i32 s7, s6, 31
	s_mul_i32 s0, s0, 0x158000
	v_and_or_b32 v2, s10, 64, v91
	s_mul_hi_i32 s13, s6, 0x5600
	s_add_u32 s0, s11, s0
	v_or_b32_e32 v2, s12, v2
	s_addc_u32 s1, s1, s13
	v_ashrrev_i32_e32 v3, 31, v2
	v_lshl_add_u64 v[2:3], v[2:3], 2, s[0:1]
	v_lshl_add_u64 v[2:3], v[2:3], 0, v[0:1]
	v_mov_b32_e32 v69, v1
	v_lshl_add_u64 v[2:3], v[2:3], 0, v[68:69]
	v_add_co_u32_e32 v4, vcc, s36, v2
	s_mov_b32 s0, 0x2b000
	s_nop 0
	v_addc_co_u32_e32 v5, vcc, 0, v3, vcc
	global_load_dwordx4 v[62:65], v[2:3], off nt
	global_load_dwordx4 v[58:61], v[4:5], off offset:2048 nt
	v_add_co_u32_e32 v4, vcc, s0, v2
	s_mov_b32 s0, 0x56000
	s_nop 0
	v_addc_co_u32_e32 v5, vcc, 0, v3, vcc
	v_add_co_u32_e32 v6, vcc, s83, v2
	v_readlane_b32 s14, v253, 30
	s_nop 0
	v_addc_co_u32_e32 v7, vcc, 0, v3, vcc
	global_load_dwordx4 v[54:57], v[4:5], off nt
	global_load_dwordx4 v[50:53], v[6:7], off offset:2048 nt
	v_add_co_u32_e32 v4, vcc, s0, v2
	s_mov_b32 s0, 0x6b000
	s_nop 0
	v_addc_co_u32_e32 v5, vcc, 0, v3, vcc
	v_add_co_u32_e32 v6, vcc, s0, v2
	s_mov_b32 s0, 0x81000
	s_nop 0
	v_addc_co_u32_e32 v7, vcc, 0, v3, vcc
	global_load_dwordx4 v[46:49], v[4:5], off nt
	global_load_dwordx4 v[42:45], v[6:7], off offset:2048 nt
	v_add_co_u32_e32 v4, vcc, s0, v2
	s_mov_b32 s0, 0x96000
	s_nop 0
	v_addc_co_u32_e32 v5, vcc, 0, v3, vcc
	v_add_co_u32_e32 v6, vcc, s0, v2
	s_mov_b32 s0, 0xac000
	s_nop 0
	v_addc_co_u32_e32 v7, vcc, 0, v3, vcc
	global_load_dwordx4 v[38:41], v[4:5], off nt
	global_load_dwordx4 v[34:37], v[6:7], off offset:2048 nt
	v_add_co_u32_e32 v4, vcc, s0, v2
	s_mov_b32 s0, 0xc1000
	s_nop 0
	v_addc_co_u32_e32 v5, vcc, 0, v3, vcc
	v_add_co_u32_e32 v6, vcc, s0, v2
	s_mov_b32 s0, 0xd7000
	s_nop 0
	v_addc_co_u32_e32 v7, vcc, 0, v3, vcc
	global_load_dwordx4 v[30:33], v[4:5], off nt
	global_load_dwordx4 v[26:29], v[6:7], off offset:2048 nt
	v_add_co_u32_e32 v4, vcc, s0, v2
	s_mov_b32 s0, 0xec000
	s_nop 0
	v_addc_co_u32_e32 v5, vcc, 0, v3, vcc
	v_add_co_u32_e32 v6, vcc, s0, v2
	s_mov_b32 s0, 0x102000
	s_nop 0
	v_addc_co_u32_e32 v7, vcc, 0, v3, vcc
	global_load_dwordx4 v[22:25], v[4:5], off nt
	global_load_dwordx4 v[18:21], v[6:7], off offset:2048 nt
	v_add_co_u32_e32 v4, vcc, s0, v2
	s_lshl_b64 s[0:1], s[6:7], 2
	s_nop 0
	v_addc_co_u32_e32 v5, vcc, 0, v3, vcc
	v_add_co_u32_e32 v6, vcc, 0x117000, v2
	v_readlane_b32 s15, v253, 31
	s_nop 0
	v_addc_co_u32_e32 v7, vcc, 0, v3, vcc
	global_load_dwordx4 v[14:17], v[4:5], off nt
	global_load_dwordx4 v[10:13], v[6:7], off offset:2048 nt
	v_add_co_u32_e32 v4, vcc, 0x12d000, v2
	s_add_u32 s12, s2, s0
	s_nop 0
	v_addc_co_u32_e32 v5, vcc, 0, v3, vcc
	v_add_co_u32_e32 v2, vcc, 0x142000, v2
	v_cndmask_b32_e64 v69, 0, 1, s[14:15]
	s_nop 0
	v_addc_co_u32_e32 v3, vcc, 0, v3, vcc
	global_load_dwordx4 v[6:9], v[4:5], off nt
	s_nop 0
	global_load_dwordx4 v[2:5], v[2:3], off offset:2048 nt
	s_addc_u32 s13, s16, s1
	v_cmp_ne_u32_e64 s[0:1], 1, v69
	s_andn2_b64 vcc, exec, s[14:15]
	v_lshlrev_b32_e32 v69, 2, v66
	s_cbranch_vccnz .LBB0_1441
	v_lshlrev_b32_e32 v156, 2, v66
	global_load_dword v140, v156, s[12:13]
	global_load_dword v141, v156, s[12:13] offset:16
	global_load_dword v142, v156, s[12:13] offset:32
	global_load_dword v143, v156, s[12:13] offset:48
	global_load_dword v144, v156, s[12:13] offset:64
	global_load_dword v145, v156, s[12:13] offset:80
	global_load_dword v146, v156, s[12:13] offset:96
	global_load_dword v147, v156, s[12:13] offset:112
	global_load_dword v148, v156, s[12:13] offset:128
	global_load_dword v149, v156, s[12:13] offset:144
	global_load_dword v150, v156, s[12:13] offset:160
	global_load_dword v151, v156, s[12:13] offset:176
	global_load_dword v152, v156, s[12:13] offset:192
	global_load_dword v153, v156, s[12:13] offset:208
	global_load_dword v154, v156, s[12:13] offset:224
	global_load_dword v155, v156, s[12:13] offset:240
	s_waitcnt vmcnt(0)
	v_mov_b32_e32 v88, v140
	s_waitcnt vmcnt(0)
	v_pk_mul_f32 v[98:99], v[62:63], v[88:89] op_sel_hi:[1,0]
	ds_write2_b32 v94, v98, v99 offset1:1
	v_pk_mul_f32 v[98:99], v[64:65], v[88:89] op_sel_hi:[1,0]
	v_mov_b32_e32 v88, v141
	ds_write2_b32 v94, v98, v99 offset0:2 offset1:3
	s_cbranch_execnz .LBB0_1421

; #define LAS __attribute__((address_space(3)))
; __device__ __forceinline__ void p0_item(const float* s0, const float* s1, int nv0, int nv1, int N, bf16* dst, int K, LAS float* scr, int lane, const float* gain  ) {
;     ...
;     for (int i = 0; i < 16; ++i) v[i] = ok ? __builtin_nontemporal_load((const f32x4*)(src + (size_t)(4 * i) * N)) : (f32x4){0.f, 0.f, 0.f, 0.f};
; #pragma unroll
;     for (int i = 0; i < 16; ++i) { const float gk = gain ? gain[4 * i + r] : 1.f; LAS float* d = scr + (4 * i + r) * 65 + 4 * c4; d[0] = v[i].x * gk; d[1] = v[i].y * gk; d[2] = v[i].z * gk; d[3] = v[i].w * gk; }
.LBB0_1421:
	s_waitcnt vmcnt(0)
	v_pk_mul_f32 v[58:59], v[58:59], v[88:89] op_sel_hi:[1,0]
	ds_write2_b32 v92, v58, v59 offset1:1
	v_pk_mul_f32 v[58:59], v[60:61], v[88:89] op_sel_hi:[1,0]
	s_and_b64 vcc, exec, s[0:1]
	ds_write2_b32 v92, v58, v59 offset0:2 offset1:3
	s_cbranch_vccnz .LBB0_1442
	v_mov_b32_e32 v58, v142
	s_waitcnt vmcnt(0)
	v_pk_mul_f32 v[60:61], v[54:55], v[58:59] op_sel_hi:[1,0]
	v_pk_mul_f32 v[58:59], v[56:57], v[58:59] op_sel_hi:[1,0]
	ds_write2_b32 v95, v58, v59 offset0:2 offset1:3
	v_mov_b32_e32 v58, v143
	ds_write2_b32 v95, v60, v61 offset1:1
	s_cbranch_execnz .LBB0_1424

; #define LAS __attribute__((address_space(3)))
; __device__ __forceinline__ void p0_item(const float* s0, const float* s1, int nv0, int nv1, int N, bf16* dst, int K, LAS float* scr, int lane, const float* gain  ) {
;     ...
;     for (int i = 0; i < 16; ++i) v[i] = ok ? __builtin_nontemporal_load((const f32x4*)(src + (size_t)(4 * i) * N)) : (f32x4){0.f, 0.f, 0.f, 0.f};
; #pragma unroll
;     for (int i = 0; i < 16; ++i) { const float gk = gain ? gain[4 * i + r] : 1.f; LAS float* d = scr + (4 * i + r) * 65 + 4 * c4; d[0] = v[i].x * gk; d[1] = v[i].y * gk; d[2] = v[i].z * gk; d[3] = v[i].w * gk; }
.LBB0_1424:
	s_waitcnt vmcnt(0)
	v_pk_mul_f32 v[50:51], v[50:51], v[58:59] op_sel_hi:[1,0]
	ds_write2_b32 v93, v50, v51 offset1:1
	v_pk_mul_f32 v[50:51], v[52:53], v[58:59] op_sel_hi:[1,0]
	s_and_b64 vcc, exec, s[0:1]
	ds_write2_b32 v93, v50, v51 offset0:2 offset1:3
	s_cbranch_vccnz .LBB0_1443
	v_mov_b32_e32 v50, v144
	s_waitcnt vmcnt(0)
	v_pk_mul_f32 v[52:53], v[46:47], v[50:51] op_sel_hi:[1,0]
	v_pk_mul_f32 v[50:51], v[48:49], v[50:51] op_sel_hi:[1,0]
	ds_write2_b32 v96, v50, v51 offset0:2 offset1:3
	v_mov_b32_e32 v50, v145
	ds_write2_b32 v96, v52, v53 offset1:1
	s_cbranch_execnz .LBB0_1427

; #define LAS __attribute__((address_space(3)))
; __device__ __forceinline__ void p0_item(const float* s0, const float* s1, int nv0, int nv1, int N, bf16* dst, int K, LAS float* scr, int lane, const float* gain  ) {
;     ...
;     for (int i = 0; i < 16; ++i) v[i] = ok ? __builtin_nontemporal_load((const f32x4*)(src + (size_t)(4 * i) * N)) : (f32x4){0.f, 0.f, 0.f, 0.f};
; #pragma unroll
;     for (int i = 0; i < 16; ++i) { const float gk = gain ? gain[4 * i + r] : 1.f; LAS float* d = scr + (4 * i + r) * 65 + 4 * c4; d[0] = v[i].x * gk; d[1] = v[i].y * gk; d[2] = v[i].z * gk; d[3] = v[i].w * gk; }
.LBB0_1427:
	s_waitcnt vmcnt(0)
	v_pk_mul_f32 v[42:43], v[42:43], v[50:51] op_sel_hi:[1,0]
	v_add_u32_e32 v46, 0x410, v96
	ds_write2_b32 v46, v42, v43 offset1:1
	v_pk_mul_f32 v[42:43], v[44:45], v[50:51] op_sel_hi:[1,0]
	v_add_u32_e32 v44, 0x418, v96
	ds_write2_b32 v44, v42, v43 offset1:1
	s_and_b64 vcc, exec, s[0:1]
	v_add_u32_e32 v43, 0x820, v96
	v_add_u32_e32 v44, 0x828, v96
	s_cbranch_vccnz .LBB0_1444
	v_mov_b32_e32 v42, v146
	s_waitcnt vmcnt(0)
	v_pk_mul_f32 v[46:47], v[38:39], v[42:43] op_sel_hi:[1,0]
	ds_write2_b32 v43, v46, v47 offset1:1
	v_pk_mul_f32 v[46:47], v[40:41], v[42:43] op_sel_hi:[1,0]
	v_mov_b32_e32 v42, v147
	ds_write2_b32 v44, v46, v47 offset1:1
	s_cbranch_execnz .LBB0_1430

; #define LAS __attribute__((address_space(3)))
; __device__ __forceinline__ void p0_item(const float* s0, const float* s1, int nv0, int nv1, int N, bf16* dst, int K, LAS float* scr, int lane, const float* gain  ) {
;     ...
;     for (int i = 0; i < 16; ++i) v[i] = ok ? __builtin_nontemporal_load((const f32x4*)(src + (size_t)(4 * i) * N)) : (f32x4){0.f, 0.f, 0.f, 0.f};
; #pragma unroll
;     for (int i = 0; i < 16; ++i) { const float gk = gain ? gain[4 * i + r] : 1.f; LAS float* d = scr + (4 * i + r) * 65 + 4 * c4; d[0] = v[i].x * gk; d[1] = v[i].y * gk; d[2] = v[i].z * gk; d[3] = v[i].w * gk; }
.LBB0_1430:
	s_waitcnt vmcnt(0)
	v_pk_mul_f32 v[34:35], v[34:35], v[42:43] op_sel_hi:[1,0]
	v_add_u32_e32 v38, 0xc30, v96
	ds_write2_b32 v38, v34, v35 offset1:1
	v_pk_mul_f32 v[34:35], v[36:37], v[42:43] op_sel_hi:[1,0]
	v_add_u32_e32 v36, 0xc38, v96
	ds_write2_b32 v36, v34, v35 offset1:1
	s_and_b64 vcc, exec, s[0:1]
	v_add_u32_e32 v35, 0x1040, v96
	v_add_u32_e32 v36, 0x1048, v96
	s_cbranch_vccnz .LBB0_1445
	v_mov_b32_e32 v34, v148
	s_waitcnt vmcnt(0)
	v_pk_mul_f32 v[38:39], v[30:31], v[34:35] op_sel_hi:[1,0]
	ds_write2_b32 v35, v38, v39 offset1:1
	v_pk_mul_f32 v[38:39], v[32:33], v[34:35] op_sel_hi:[1,0]
	v_mov_b32_e32 v34, v149
	ds_write2_b32 v36, v38, v39 offset1:1
	s_cbranch_execnz .LBB0_1433

; #define LAS __attribute__((address_space(3)))
; __device__ __forceinline__ void p0_item(const float* s0, const float* s1, int nv0, int nv1, int N, bf16* dst, int K, LAS float* scr, int lane, const float* gain  ) {
;     ...
;     for (int i = 0; i < 16; ++i) v[i] = ok ? __builtin_nontemporal_load((const f32x4*)(src + (size_t)(4 * i) * N)) : (f32x4){0.f, 0.f, 0.f, 0.f};
; #pragma unroll
;     for (int i = 0; i < 16; ++i) { const float gk = gain ? gain[4 * i + r] : 1.f; LAS float* d = scr + (4 * i + r) * 65 + 4 * c4; d[0] = v[i].x * gk; d[1] = v[i].y * gk; d[2] = v[i].z * gk; d[3] = v[i].w * gk; }
.LBB0_1433:
	s_waitcnt vmcnt(0)
	v_pk_mul_f32 v[26:27], v[26:27], v[34:35] op_sel_hi:[1,0]
	v_add_u32_e32 v30, 0x1450, v96
	ds_write2_b32 v30, v26, v27 offset1:1
	v_pk_mul_f32 v[26:27], v[28:29], v[34:35] op_sel_hi:[1,0]
	v_add_u32_e32 v28, 0x1458, v96
	ds_write2_b32 v28, v26, v27 offset1:1
	s_and_b64 vcc, exec, s[0:1]
	v_add_u32_e32 v27, 0x1860, v96
	v_add_u32_e32 v28, 0x1868, v96
	s_cbranch_vccnz .LBB0_1446
	v_mov_b32_e32 v26, v150
	s_waitcnt vmcnt(0)
	v_pk_mul_f32 v[30:31], v[22:23], v[26:27] op_sel_hi:[1,0]
	ds_write2_b32 v27, v30, v31 offset1:1
	v_pk_mul_f32 v[30:31], v[24:25], v[26:27] op_sel_hi:[1,0]
	v_mov_b32_e32 v26, v151
	ds_write2_b32 v28, v30, v31 offset1:1
	s_cbranch_execnz .LBB0_1436

; #define LAS __attribute__((address_space(3)))
; __device__ __forceinline__ void p0_item(const float* s0, const float* s1, int nv0, int nv1, int N, bf16* dst, int K, LAS float* scr, int lane, const float* gain  ) {
;     ...
;     for (int i = 0; i < 16; ++i) v[i] = ok ? __builtin_nontemporal_load((const f32x4*)(src + (size_t)(4 * i) * N)) : (f32x4){0.f, 0.f, 0.f, 0.f};
; #pragma unroll
;     for (int i = 0; i < 16; ++i) { const float gk = gain ? gain[4 * i + r] : 1.f; LAS float* d = scr + (4 * i + r) * 65 + 4 * c4; d[0] = v[i].x * gk; d[1] = v[i].y * gk; d[2] = v[i].z * gk; d[3] = v[i].w * gk; }
.LBB0_1436:
	s_waitcnt vmcnt(0)
	v_pk_mul_f32 v[18:19], v[18:19], v[26:27] op_sel_hi:[1,0]
	v_add_u32_e32 v22, 0x1c70, v96
	ds_write2_b32 v22, v18, v19 offset1:1
	v_pk_mul_f32 v[18:19], v[20:21], v[26:27] op_sel_hi:[1,0]
	v_add_u32_e32 v20, 0x1c78, v96
	ds_write2_b32 v20, v18, v19 offset1:1
	s_and_b64 vcc, exec, s[0:1]
	v_add_u32_e32 v19, 0x2080, v96
	v_add_u32_e32 v20, 0x2088, v96
	s_cbranch_vccnz .LBB0_1447
	v_mov_b32_e32 v18, v152
	s_waitcnt vmcnt(0)
	v_pk_mul_f32 v[22:23], v[14:15], v[18:19] op_sel_hi:[1,0]
	ds_write2_b32 v19, v22, v23 offset1:1
	v_pk_mul_f32 v[22:23], v[16:17], v[18:19] op_sel_hi:[1,0]
	v_mov_b32_e32 v18, v153
	ds_write2_b32 v20, v22, v23 offset1:1
	s_cbranch_execnz .LBB0_1439

; #define LAS __attribute__((address_space(3)))
; __device__ __forceinline__ void p0_item(const float* s0, const float* s1, int nv0, int nv1, int N, bf16* dst, int K, LAS float* scr, int lane, const float* gain  ) {
;     ...
;     for (int i = 0; i < 16; ++i) v[i] = ok ? __builtin_nontemporal_load((const f32x4*)(src + (size_t)(4 * i) * N)) : (f32x4){0.f, 0.f, 0.f, 0.f};
; #pragma unroll
;     for (int i = 0; i < 16; ++i) { const float gk = gain ? gain[4 * i + r] : 1.f; LAS float* d = scr + (4 * i + r) * 65 + 4 * c4; d[0] = v[i].x * gk; d[1] = v[i].y * gk; d[2] = v[i].z * gk; d[3] = v[i].w * gk; }
.LBB0_1439:
	s_waitcnt vmcnt(0)
	v_pk_mul_f32 v[10:11], v[10:11], v[18:19] op_sel_hi:[1,0]
	v_add_u32_e32 v14, 0x2490, v96
	ds_write2_b32 v14, v10, v11 offset1:1
	v_pk_mul_f32 v[10:11], v[12:13], v[18:19] op_sel_hi:[1,0]
	v_add_u32_e32 v12, 0x2498, v96
	ds_write2_b32 v12, v10, v11 offset1:1
	s_and_b64 vcc, exec, s[0:1]
	v_add_u32_e32 v11, 0x28a0, v96
	v_add_u32_e32 v12, 0x28a8, v96
	s_cbranch_vccnz .LBB0_1448
	v_mov_b32_e32 v10, v154
	s_waitcnt vmcnt(0)
	v_pk_mul_f32 v[14:15], v[6:7], v[10:11] op_sel_hi:[1,0]
	ds_write2_b32 v11, v14, v15 offset1:1
	v_pk_mul_f32 v[14:15], v[8:9], v[10:11] op_sel_hi:[1,0]
	v_mov_b32_e32 v10, v155
	ds_write2_b32 v12, v14, v15 offset1:1
	s_cbranch_execnz .LBB0_1417
	s_branch .LBB0_1449

; #define LAS __attribute__((address_space(3)))
; __device__ __forceinline__ void p0_item(const float* s0, const float* s1, int nv0, int nv1, int N, bf16* dst, int K, LAS float* scr, int lane, const float* gain  ) {
;     const int r = lane >> 4, c4 = lane & 15, hf = c4 >> 3, cc = (c4 & 7) * 4;
;     const float* src = (hf ? s1 : s0) + (size_t)r * N + cc;
;     const bool ok = cc < (hf ? nv1 : nv0);
;     f32x4 v[16];
; #pragma unroll
;     for (int i = 0; i < 16; ++i) v[i] = ok ? __builtin_nontemporal_load((const f32x4*)(src + (size_t)(4 * i) * N)) : (f32x4){0.f, 0.f, 0.f, 0.f};
; #pragma unroll
;     for (int i = 0; i < 16; ++i) { const float gk = gain ? gain[4 * i + r] : 1.f; LAS float* d = scr + (4 * i + r) * 65 + 4 * c4; d[0] = v[i].x * gk; d[1] = v[i].y * gk; d[2] = v[i].z * gk; d[3] = v[i].w * gk; }
.LBB0_1518:
	s_or_b64 exec, exec, s[14:15]
	s_ashr_i32 s13, s12, 31
	v_readlane_b32 s16, v253, 36
	s_lshl_b64 s[6:7], s[12:13], 2
	v_readlane_b32 s17, v253, 37
	s_add_u32 s14, s26, s6
	s_addc_u32 s15, s27, s7
	v_cndmask_b32_e64 v71, 0, 1, s[16:17]
	v_cmp_ne_u32_e64 s[6:7], 1, v71
	s_andn2_b64 vcc, exec, s[16:17]
	v_lshlrev_b32_e32 v71, 2, v66
	s_cbranch_vccnz .LBB0_1541
	v_lshlrev_b32_e32 v156, 2, v66
	global_load_dword v140, v156, s[14:15]
	global_load_dword v141, v156, s[14:15] offset:16
	global_load_dword v142, v156, s[14:15] offset:32
	global_load_dword v143, v156, s[14:15] offset:48
	global_load_dword v144, v156, s[14:15] offset:64
	global_load_dword v145, v156, s[14:15] offset:80
	global_load_dword v146, v156, s[14:15] offset:96
	global_load_dword v147, v156, s[14:15] offset:112
	global_load_dword v148, v156, s[14:15] offset:128
	global_load_dword v149, v156, s[14:15] offset:144
	global_load_dword v150, v156, s[14:15] offset:160
	global_load_dword v151, v156, s[14:15] offset:176
	global_load_dword v152, v156, s[14:15] offset:192
	global_load_dword v153, v156, s[14:15] offset:208
	global_load_dword v154, v156, s[14:15] offset:224
	global_load_dword v155, v156, s[14:15] offset:240
	s_waitcnt vmcnt(0)
	v_mov_b32_e32 v88, v140
	s_waitcnt vmcnt(0)
	v_pk_mul_f32 v[96:97], v[62:63], v[88:89] op_sel_hi:[1,0]
	v_pk_mul_f32 v[88:89], v[64:65], v[88:89] op_sel_hi:[1,0]
	ds_write2_b32 v92, v88, v89 offset0:2 offset1:3
	v_mov_b32_e32 v88, v141
	ds_write2_b32 v92, v96, v97 offset1:1
	s_cbranch_execnz .LBB0_1521

; #define LAS __attribute__((address_space(3)))
; __device__ __forceinline__ void p0_item(const float* s0, const float* s1, int nv0, int nv1, int N, bf16* dst, int K, LAS float* scr, int lane, const float* gain  ) {
;     ...
;     for (int i = 0; i < 16; ++i) v[i] = ok ? __builtin_nontemporal_load((const f32x4*)(src + (size_t)(4 * i) * N)) : (f32x4){0.f, 0.f, 0.f, 0.f};
; #pragma unroll
;     for (int i = 0; i < 16; ++i) { const float gk = gain ? gain[4 * i + r] : 1.f; LAS float* d = scr + (4 * i + r) * 65 + 4 * c4; d[0] = v[i].x * gk; d[1] = v[i].y * gk; d[2] = v[i].z * gk; d[3] = v[i].w * gk; }
.LBB0_1521:
	s_waitcnt vmcnt(0)
	v_pk_mul_f32 v[58:59], v[58:59], v[88:89] op_sel_hi:[1,0]
	ds_write2_b32 v69, v58, v59 offset1:1
	v_pk_mul_f32 v[58:59], v[60:61], v[88:89] op_sel_hi:[1,0]
	s_and_b64 vcc, exec, s[6:7]
	ds_write2_b32 v69, v58, v59 offset0:2 offset1:3
	s_cbranch_vccnz .LBB0_1542
	v_mov_b32_e32 v58, v142
	s_waitcnt vmcnt(0)
	v_pk_mul_f32 v[60:61], v[54:55], v[58:59] op_sel_hi:[1,0]
	v_pk_mul_f32 v[58:59], v[56:57], v[58:59] op_sel_hi:[1,0]
	ds_write2_b32 v93, v58, v59 offset0:2 offset1:3
	v_mov_b32_e32 v58, v143
	ds_write2_b32 v93, v60, v61 offset1:1
	s_cbranch_execnz .LBB0_1524

; #define LAS __attribute__((address_space(3)))
; __device__ __forceinline__ void p0_item(const float* s0, const float* s1, int nv0, int nv1, int N, bf16* dst, int K, LAS float* scr, int lane, const float* gain  ) {
;     ...
;     for (int i = 0; i < 16; ++i) v[i] = ok ? __builtin_nontemporal_load((const f32x4*)(src + (size_t)(4 * i) * N)) : (f32x4){0.f, 0.f, 0.f, 0.f};
; #pragma unroll
;     for (int i = 0; i < 16; ++i) { const float gk = gain ? gain[4 * i + r] : 1.f; LAS float* d = scr + (4 * i + r) * 65 + 4 * c4; d[0] = v[i].x * gk; d[1] = v[i].y * gk; d[2] = v[i].z * gk; d[3] = v[i].w * gk; }
.LBB0_1524:
	s_waitcnt vmcnt(0)
	v_pk_mul_f32 v[46:47], v[46:47], v[58:59] op_sel_hi:[1,0]
	ds_write2_b32 v91, v46, v47 offset1:1
	v_pk_mul_f32 v[46:47], v[48:49], v[58:59] op_sel_hi:[1,0]
	s_and_b64 vcc, exec, s[6:7]
	ds_write2_b32 v91, v46, v47 offset0:2 offset1:3
	s_cbranch_vccnz .LBB0_1543
	v_mov_b32_e32 v46, v144
	s_waitcnt vmcnt(0)
	v_pk_mul_f32 v[48:49], v[50:51], v[46:47] op_sel_hi:[1,0]
	v_pk_mul_f32 v[46:47], v[52:53], v[46:47] op_sel_hi:[1,0]
	ds_write2_b32 v94, v46, v47 offset0:2 offset1:3
	v_mov_b32_e32 v46, v145
	ds_write2_b32 v94, v48, v49 offset1:1
	s_cbranch_execnz .LBB0_1527

; #define LAS __attribute__((address_space(3)))
; __device__ __forceinline__ void p0_item(const float* s0, const float* s1, int nv0, int nv1, int N, bf16* dst, int K, LAS float* scr, int lane, const float* gain  ) {
;     ...
;     for (int i = 0; i < 16; ++i) v[i] = ok ? __builtin_nontemporal_load((const f32x4*)(src + (size_t)(4 * i) * N)) : (f32x4){0.f, 0.f, 0.f, 0.f};
; #pragma unroll
;     for (int i = 0; i < 16; ++i) { const float gk = gain ? gain[4 * i + r] : 1.f; LAS float* d = scr + (4 * i + r) * 65 + 4 * c4; d[0] = v[i].x * gk; d[1] = v[i].y * gk; d[2] = v[i].z * gk; d[3] = v[i].w * gk; }
.LBB0_1527:
	s_waitcnt vmcnt(0)
	v_pk_mul_f32 v[38:39], v[38:39], v[46:47] op_sel_hi:[1,0]
	v_add_u32_e32 v47, 0x410, v94
	ds_write2_b32 v47, v38, v39 offset1:1
	v_pk_mul_f32 v[38:39], v[40:41], v[46:47] op_sel_hi:[1,0]
	v_add_u32_e32 v40, 0x418, v94
	ds_write2_b32 v40, v38, v39 offset1:1
	s_and_b64 vcc, exec, s[6:7]
	v_add_u32_e32 v39, 0x820, v94
	v_add_u32_e32 v40, 0x828, v94
	s_cbranch_vccnz .LBB0_1544
	v_mov_b32_e32 v38, v146
	s_waitcnt vmcnt(0)
	v_pk_mul_f32 v[46:47], v[42:43], v[38:39] op_sel_hi:[1,0]
	ds_write2_b32 v39, v46, v47 offset1:1
	v_pk_mul_f32 v[46:47], v[44:45], v[38:39] op_sel_hi:[1,0]
	v_mov_b32_e32 v38, v147
	ds_write2_b32 v40, v46, v47 offset1:1
	s_cbranch_execnz .LBB0_1530

; #define LAS __attribute__((address_space(3)))
; __device__ __forceinline__ void p0_item(const float* s0, const float* s1, int nv0, int nv1, int N, bf16* dst, int K, LAS float* scr, int lane, const float* gain  ) {
;     ...
;     for (int i = 0; i < 16; ++i) v[i] = ok ? __builtin_nontemporal_load((const f32x4*)(src + (size_t)(4 * i) * N)) : (f32x4){0.f, 0.f, 0.f, 0.f};
; #pragma unroll
;     for (int i = 0; i < 16; ++i) { const float gk = gain ? gain[4 * i + r] : 1.f; LAS float* d = scr + (4 * i + r) * 65 + 4 * c4; d[0] = v[i].x * gk; d[1] = v[i].y * gk; d[2] = v[i].z * gk; d[3] = v[i].w * gk; }
.LBB0_1530:
	s_waitcnt vmcnt(0)
	v_pk_mul_f32 v[30:31], v[30:31], v[38:39] op_sel_hi:[1,0]
	v_add_u32_e32 v39, 0xc30, v94
	ds_write2_b32 v39, v30, v31 offset1:1
	v_pk_mul_f32 v[30:31], v[32:33], v[38:39] op_sel_hi:[1,0]
	v_add_u32_e32 v32, 0xc38, v94
	ds_write2_b32 v32, v30, v31 offset1:1
	s_and_b64 vcc, exec, s[6:7]
	v_add_u32_e32 v31, 0x1040, v94
	v_add_u32_e32 v32, 0x1048, v94
	s_cbranch_vccnz .LBB0_1545
	v_mov_b32_e32 v30, v148
	s_waitcnt vmcnt(0)
	v_pk_mul_f32 v[38:39], v[34:35], v[30:31] op_sel_hi:[1,0]
	ds_write2_b32 v31, v38, v39 offset1:1
	v_pk_mul_f32 v[38:39], v[36:37], v[30:31] op_sel_hi:[1,0]
	v_mov_b32_e32 v30, v149
	ds_write2_b32 v32, v38, v39 offset1:1
	s_cbranch_execnz .LBB0_1533

; #define LAS __attribute__((address_space(3)))
; __device__ __forceinline__ void p0_item(const float* s0, const float* s1, int nv0, int nv1, int N, bf16* dst, int K, LAS float* scr, int lane, const float* gain  ) {
;     ...
;     for (int i = 0; i < 16; ++i) v[i] = ok ? __builtin_nontemporal_load((const f32x4*)(src + (size_t)(4 * i) * N)) : (f32x4){0.f, 0.f, 0.f, 0.f};
; #pragma unroll
;     for (int i = 0; i < 16; ++i) { const float gk = gain ? gain[4 * i + r] : 1.f; LAS float* d = scr + (4 * i + r) * 65 + 4 * c4; d[0] = v[i].x * gk; d[1] = v[i].y * gk; d[2] = v[i].z * gk; d[3] = v[i].w * gk; }
.LBB0_1533:
	s_waitcnt vmcnt(0)
	v_pk_mul_f32 v[22:23], v[22:23], v[30:31] op_sel_hi:[1,0]
	v_add_u32_e32 v31, 0x1450, v94
	ds_write2_b32 v31, v22, v23 offset1:1
	v_pk_mul_f32 v[22:23], v[24:25], v[30:31] op_sel_hi:[1,0]
	v_add_u32_e32 v24, 0x1458, v94
	ds_write2_b32 v24, v22, v23 offset1:1
	s_and_b64 vcc, exec, s[6:7]
	v_add_u32_e32 v23, 0x1860, v94
	v_add_u32_e32 v24, 0x1868, v94
	s_cbranch_vccnz .LBB0_1546
	v_mov_b32_e32 v22, v150
	s_waitcnt vmcnt(0)
	v_pk_mul_f32 v[30:31], v[26:27], v[22:23] op_sel_hi:[1,0]
	ds_write2_b32 v23, v30, v31 offset1:1
	v_pk_mul_f32 v[30:31], v[28:29], v[22:23] op_sel_hi:[1,0]
	v_mov_b32_e32 v22, v151
	ds_write2_b32 v24, v30, v31 offset1:1
	s_cbranch_execnz .LBB0_1536

; #define LAS __attribute__((address_space(3)))
; __device__ __forceinline__ void p0_item(const float* s0, const float* s1, int nv0, int nv1, int N, bf16* dst, int K, LAS float* scr, int lane, const float* gain  ) {
;     ...
;     for (int i = 0; i < 16; ++i) v[i] = ok ? __builtin_nontemporal_load((const f32x4*)(src + (size_t)(4 * i) * N)) : (f32x4){0.f, 0.f, 0.f, 0.f};
; #pragma unroll
;     for (int i = 0; i < 16; ++i) { const float gk = gain ? gain[4 * i + r] : 1.f; LAS float* d = scr + (4 * i + r) * 65 + 4 * c4; d[0] = v[i].x * gk; d[1] = v[i].y * gk; d[2] = v[i].z * gk; d[3] = v[i].w * gk; }
.LBB0_1536:
	s_waitcnt vmcnt(0)
	v_pk_mul_f32 v[14:15], v[14:15], v[22:23] op_sel_hi:[1,0]
	v_add_u32_e32 v23, 0x1c70, v94
	ds_write2_b32 v23, v14, v15 offset1:1
	v_pk_mul_f32 v[14:15], v[16:17], v[22:23] op_sel_hi:[1,0]
	v_add_u32_e32 v16, 0x1c78, v94
	ds_write2_b32 v16, v14, v15 offset1:1
	s_and_b64 vcc, exec, s[6:7]
	v_add_u32_e32 v15, 0x2080, v94
	v_add_u32_e32 v16, 0x2088, v94
	s_cbranch_vccnz .LBB0_1547
	v_mov_b32_e32 v14, v152
	s_waitcnt vmcnt(0)
	v_pk_mul_f32 v[22:23], v[18:19], v[14:15] op_sel_hi:[1,0]
	ds_write2_b32 v15, v22, v23 offset1:1
	v_pk_mul_f32 v[22:23], v[20:21], v[14:15] op_sel_hi:[1,0]
	v_mov_b32_e32 v14, v153
	ds_write2_b32 v16, v22, v23 offset1:1
	s_cbranch_execnz .LBB0_1539

; #define LAS __attribute__((address_space(3)))
; __device__ __forceinline__ void p0_item(const float* s0, const float* s1, int nv0, int nv1, int N, bf16* dst, int K, LAS float* scr, int lane, const float* gain  ) {
;     ...
;     for (int i = 0; i < 16; ++i) v[i] = ok ? __builtin_nontemporal_load((const f32x4*)(src + (size_t)(4 * i) * N)) : (f32x4){0.f, 0.f, 0.f, 0.f};
; #pragma unroll
;     for (int i = 0; i < 16; ++i) { const float gk = gain ? gain[4 * i + r] : 1.f; LAS float* d = scr + (4 * i + r) * 65 + 4 * c4; d[0] = v[i].x * gk; d[1] = v[i].y * gk; d[2] = v[i].z * gk; d[3] = v[i].w * gk; }
.LBB0_1539:
	s_waitcnt vmcnt(0)
	v_pk_mul_f32 v[6:7], v[6:7], v[14:15] op_sel_hi:[1,0]
	v_add_u32_e32 v15, 0x2490, v94
	ds_write2_b32 v15, v6, v7 offset1:1
	v_pk_mul_f32 v[6:7], v[8:9], v[14:15] op_sel_hi:[1,0]
	v_add_u32_e32 v8, 0x2498, v94
	ds_write2_b32 v8, v6, v7 offset1:1
	s_and_b64 vcc, exec, s[6:7]
	v_add_u32_e32 v7, 0x28a0, v94
	v_add_u32_e32 v8, 0x28a8, v94
	s_cbranch_vccnz .LBB0_1548
	v_mov_b32_e32 v6, v154
	s_waitcnt vmcnt(0)
	v_pk_mul_f32 v[14:15], v[10:11], v[6:7] op_sel_hi:[1,0]
	ds_write2_b32 v7, v14, v15 offset1:1
	v_pk_mul_f32 v[14:15], v[12:13], v[6:7] op_sel_hi:[1,0]
	v_mov_b32_e32 v6, v155
	ds_write2_b32 v8, v14, v15 offset1:1
	s_cbranch_execnz .LBB0_1453
	s_branch .LBB0_1549

; #define LAS __attribute__((address_space(3)))
; __device__ __forceinline__ void p0_item(const float* s0, const float* s1, int nv0, int nv1, int N, bf16* dst, int K, LAS float* scr, int lane, const float* gain  ) {
;     const int r = lane >> 4, c4 = lane & 15, hf = c4 >> 3, cc = (c4 & 7) * 4;
;     const float* src = (hf ? s1 : s0) + (size_t)r * N + cc;
;     const bool ok = cc < (hf ? nv1 : nv0);
;     f32x4 v[16];
; #pragma unroll
;     for (int i = 0; i < 16; ++i) v[i] = ok ? __builtin_nontemporal_load((const f32x4*)(src + (size_t)(4 * i) * N)) : (f32x4){0.f, 0.f, 0.f, 0.f};
; #pragma unroll
;     for (int i = 0; i < 16; ++i) { const float gk = gain ? gain[4 * i + r] : 1.f; LAS float* d = scr + (4 * i + r) * 65 + 4 * c4; d[0] = v[i].x * gk; d[1] = v[i].y * gk; d[2] = v[i].z * gk; d[3] = v[i].w * gk; }
; __device__ __forceinline__ void p0_matrix(int type  , const float* W0, const float* W1, int K, int Nsrc, int Ndst, bf16* dst, LAS float* scr, int gw, int NGW, int lane, const float* gain) {
;     const int nruns = Ndst >> 6, nitems = (K >> 6) * nruns;
;     for (int it = gw; it < nitems; it += NGW) {
;         const int kb = it / nruns, nb = it - kb * nruns, n0 = nb * 64, k0 = kb * 64;
;         const float* src = W0; int c0 = n0, c1 = n0 + 32, nv0 = 32, nv1 = 32;
;         if (type == 1) { const int tile = n0 >> 8, r = n0 & 255; src = r < 128 ? W0 : W1; c0 = tile * 128 + (r & 127); c1 = c0 + 32; }
;         else if (type == 2) { c0 = win_src_col(n0, nv0); c1 = win_src_col(n0 + 32, nv1); }
;         const float* rowp = src + (size_t)k0 * Nsrc;
;         p0_item(rowp + c0, rowp + c1, nv0, nv1, Nsrc, dst + (size_t)n0 * K + k0, K, scr, lane, gain ? gain + k0 : nullptr);
.LBB0_1569:
	s_mul_hi_i32 s0, s28, 0x2fa0be83
	s_lshr_b32 s1, s0, 31
	s_ashr_i32 s0, s0, 5
	s_add_i32 s0, s0, s1
	s_mul_i32 s1, s0, 0xffffd500
	s_add_i32 s10, s26, s1
	s_lshl_b32 s6, s0, 6
	s_bitcmp0_b32 s28, 1
	s_cselect_b32 s7, s48, s50
	s_mul_i32 s11, s20, 0x2b00000
	s_cselect_b32 s1, s49, s51
	s_add_u32 s11, s7, s11
	s_mul_i32 s7, s0, 0xffffea80
	s_addc_u32 s1, s1, 0
	s_add_i32 s7, s24, s7
	s_and_b32 s12, s7, 0xffffff80
	s_ashr_i32 s7, s6, 31
	s_mul_i32 s0, s0, 0x158000
	v_and_or_b32 v2, s10, 64, v89
	s_mul_hi_i32 s13, s6, 0x5600
	s_add_u32 s0, s11, s0
	v_or_b32_e32 v2, s12, v2
	s_addc_u32 s1, s1, s13
	v_ashrrev_i32_e32 v3, 31, v2
	v_lshl_add_u64 v[2:3], v[2:3], 2, s[0:1]
	v_lshl_add_u64 v[2:3], v[2:3], 0, v[0:1]
	v_mov_b32_e32 v69, v1
	v_lshl_add_u64 v[2:3], v[2:3], 0, v[68:69]
	v_add_co_u32_e32 v4, vcc, s36, v2
	s_mov_b32 s0, 0x2b000
	s_nop 0
	v_addc_co_u32_e32 v5, vcc, 0, v3, vcc
	global_load_dwordx4 v[62:65], v[2:3], off nt
	global_load_dwordx4 v[58:61], v[4:5], off offset:2048 nt
	v_add_co_u32_e32 v4, vcc, s0, v2
	s_mov_b32 s0, 0x56000
	s_nop 0
	v_addc_co_u32_e32 v5, vcc, 0, v3, vcc
	v_add_co_u32_e32 v6, vcc, s83, v2
	v_readlane_b32 s14, v253, 38
	s_nop 0
	v_addc_co_u32_e32 v7, vcc, 0, v3, vcc
	global_load_dwordx4 v[54:57], v[4:5], off nt
	global_load_dwordx4 v[50:53], v[6:7], off offset:2048 nt
	v_add_co_u32_e32 v4, vcc, s0, v2
	s_mov_b32 s0, 0x6b000
	s_nop 0
	v_addc_co_u32_e32 v5, vcc, 0, v3, vcc
	v_add_co_u32_e32 v6, vcc, s0, v2
	s_mov_b32 s0, 0x81000
	s_nop 0
	v_addc_co_u32_e32 v7, vcc, 0, v3, vcc
	global_load_dwordx4 v[46:49], v[4:5], off nt
	global_load_dwordx4 v[42:45], v[6:7], off offset:2048 nt
	v_add_co_u32_e32 v4, vcc, s0, v2
	s_mov_b32 s0, 0x96000
	s_nop 0
	v_addc_co_u32_e32 v5, vcc, 0, v3, vcc
	v_add_co_u32_e32 v6, vcc, s0, v2
	s_mov_b32 s0, 0xac000
	s_nop 0
	v_addc_co_u32_e32 v7, vcc, 0, v3, vcc
	global_load_dwordx4 v[38:41], v[4:5], off nt
	global_load_dwordx4 v[34:37], v[6:7], off offset:2048 nt
	v_add_co_u32_e32 v4, vcc, s0, v2
	s_mov_b32 s0, 0xc1000
	s_nop 0
	v_addc_co_u32_e32 v5, vcc, 0, v3, vcc
	v_add_co_u32_e32 v6, vcc, s0, v2
	s_mov_b32 s0, 0xd7000
	s_nop 0
	v_addc_co_u32_e32 v7, vcc, 0, v3, vcc
	global_load_dwordx4 v[30:33], v[4:5], off nt
	global_load_dwordx4 v[26:29], v[6:7], off offset:2048 nt
	v_add_co_u32_e32 v4, vcc, s0, v2
	s_mov_b32 s0, 0xec000
	s_nop 0
	v_addc_co_u32_e32 v5, vcc, 0, v3, vcc
	v_add_co_u32_e32 v6, vcc, s0, v2
	s_mov_b32 s0, 0x102000
	s_nop 0
	v_addc_co_u32_e32 v7, vcc, 0, v3, vcc
	global_load_dwordx4 v[22:25], v[4:5], off nt
	global_load_dwordx4 v[18:21], v[6:7], off offset:2048 nt
	v_add_co_u32_e32 v4, vcc, s0, v2
	s_lshl_b64 s[0:1], s[6:7], 2
	s_nop 0
	v_addc_co_u32_e32 v5, vcc, 0, v3, vcc
	v_add_co_u32_e32 v6, vcc, 0x117000, v2
	v_readlane_b32 s15, v253, 39
	s_nop 0
	v_addc_co_u32_e32 v7, vcc, 0, v3, vcc
	global_load_dwordx4 v[14:17], v[4:5], off nt
	global_load_dwordx4 v[10:13], v[6:7], off offset:2048 nt
	v_add_co_u32_e32 v4, vcc, 0x12d000, v2
	s_add_u32 s12, s17, s0
	s_nop 0
	v_addc_co_u32_e32 v5, vcc, 0, v3, vcc
	v_add_co_u32_e32 v2, vcc, 0x142000, v2
	v_cndmask_b32_e64 v69, 0, 1, s[14:15]
	s_nop 0
	v_addc_co_u32_e32 v3, vcc, 0, v3, vcc
	global_load_dwordx4 v[6:9], v[4:5], off nt
	s_nop 0
	global_load_dwordx4 v[2:5], v[2:3], off offset:2048 nt
	s_addc_u32 s13, s23, s1
	v_cmp_ne_u32_e64 s[0:1], 1, v69
	s_andn2_b64 vcc, exec, s[14:15]
	v_lshlrev_b32_e32 v69, 2, v66
	s_cbranch_vccnz .LBB0_1592
	v_lshlrev_b32_e32 v156, 2, v66
	global_load_dword v140, v156, s[12:13]
	global_load_dword v141, v156, s[12:13] offset:16
	global_load_dword v142, v156, s[12:13] offset:32
	global_load_dword v143, v156, s[12:13] offset:48
	global_load_dword v144, v156, s[12:13] offset:64
	global_load_dword v145, v156, s[12:13] offset:80
	global_load_dword v146, v156, s[12:13] offset:96
	global_load_dword v147, v156, s[12:13] offset:112
	global_load_dword v148, v156, s[12:13] offset:128
	global_load_dword v149, v156, s[12:13] offset:144
	global_load_dword v150, v156, s[12:13] offset:160
	global_load_dword v151, v156, s[12:13] offset:176
	global_load_dword v152, v156, s[12:13] offset:192
	global_load_dword v153, v156, s[12:13] offset:208
	global_load_dword v154, v156, s[12:13] offset:224
	global_load_dword v155, v156, s[12:13] offset:240
	s_waitcnt vmcnt(0)
	v_mov_b32_e32 v88, v140
	s_waitcnt vmcnt(0)
	v_pk_mul_f32 v[96:97], v[62:63], v[88:89] op_sel_hi:[1,0]
	ds_write2_b32 v93, v96, v97 offset1:1
	v_pk_mul_f32 v[96:97], v[64:65], v[88:89] op_sel_hi:[1,0]
	v_mov_b32_e32 v88, v141
	ds_write2_b32 v93, v96, v97 offset0:2 offset1:3
	s_cbranch_execnz .LBB0_1572

; #define LAS __attribute__((address_space(3)))
; __device__ __forceinline__ void p0_item(const float* s0, const float* s1, int nv0, int nv1, int N, bf16* dst, int K, LAS float* scr, int lane, const float* gain  ) {
;     ...
;     for (int i = 0; i < 16; ++i) v[i] = ok ? __builtin_nontemporal_load((const f32x4*)(src + (size_t)(4 * i) * N)) : (f32x4){0.f, 0.f, 0.f, 0.f};
; #pragma unroll
;     for (int i = 0; i < 16; ++i) { const float gk = gain ? gain[4 * i + r] : 1.f; LAS float* d = scr + (4 * i + r) * 65 + 4 * c4; d[0] = v[i].x * gk; d[1] = v[i].y * gk; d[2] = v[i].z * gk; d[3] = v[i].w * gk; }
.LBB0_1572:
	s_waitcnt vmcnt(0)
	v_pk_mul_f32 v[58:59], v[58:59], v[88:89] op_sel_hi:[1,0]
	ds_write2_b32 v91, v58, v59 offset1:1
	v_pk_mul_f32 v[58:59], v[60:61], v[88:89] op_sel_hi:[1,0]
	s_and_b64 vcc, exec, s[0:1]
	ds_write2_b32 v91, v58, v59 offset0:2 offset1:3
	s_cbranch_vccnz .LBB0_1593
	v_mov_b32_e32 v58, v142
	s_waitcnt vmcnt(0)
	v_pk_mul_f32 v[60:61], v[54:55], v[58:59] op_sel_hi:[1,0]
	v_pk_mul_f32 v[58:59], v[56:57], v[58:59] op_sel_hi:[1,0]
	ds_write2_b32 v94, v58, v59 offset0:2 offset1:3
	v_mov_b32_e32 v58, v143
	ds_write2_b32 v94, v60, v61 offset1:1
	s_cbranch_execnz .LBB0_1575

; #define LAS __attribute__((address_space(3)))
; __device__ __forceinline__ void p0_item(const float* s0, const float* s1, int nv0, int nv1, int N, bf16* dst, int K, LAS float* scr, int lane, const float* gain  ) {
;     ...
;     for (int i = 0; i < 16; ++i) v[i] = ok ? __builtin_nontemporal_load((const f32x4*)(src + (size_t)(4 * i) * N)) : (f32x4){0.f, 0.f, 0.f, 0.f};
; #pragma unroll
;     for (int i = 0; i < 16; ++i) { const float gk = gain ? gain[4 * i + r] : 1.f; LAS float* d = scr + (4 * i + r) * 65 + 4 * c4; d[0] = v[i].x * gk; d[1] = v[i].y * gk; d[2] = v[i].z * gk; d[3] = v[i].w * gk; }
.LBB0_1575:
	s_waitcnt vmcnt(0)
	v_pk_mul_f32 v[50:51], v[50:51], v[58:59] op_sel_hi:[1,0]
	ds_write2_b32 v92, v50, v51 offset1:1
	v_pk_mul_f32 v[50:51], v[52:53], v[58:59] op_sel_hi:[1,0]
	s_and_b64 vcc, exec, s[0:1]
	ds_write2_b32 v92, v50, v51 offset0:2 offset1:3
	s_cbranch_vccnz .LBB0_1594
	v_mov_b32_e32 v50, v144
	s_waitcnt vmcnt(0)
	v_pk_mul_f32 v[52:53], v[46:47], v[50:51] op_sel_hi:[1,0]
	v_pk_mul_f32 v[50:51], v[48:49], v[50:51] op_sel_hi:[1,0]
	ds_write2_b32 v95, v50, v51 offset0:2 offset1:3
	v_mov_b32_e32 v50, v145
	ds_write2_b32 v95, v52, v53 offset1:1
	s_cbranch_execnz .LBB0_1578

; #define LAS __attribute__((address_space(3)))
; __device__ __forceinline__ void p0_item(const float* s0, const float* s1, int nv0, int nv1, int N, bf16* dst, int K, LAS float* scr, int lane, const float* gain  ) {
;     ...
;     for (int i = 0; i < 16; ++i) v[i] = ok ? __builtin_nontemporal_load((const f32x4*)(src + (size_t)(4 * i) * N)) : (f32x4){0.f, 0.f, 0.f, 0.f};
; #pragma unroll
;     for (int i = 0; i < 16; ++i) { const float gk = gain ? gain[4 * i + r] : 1.f; LAS float* d = scr + (4 * i + r) * 65 + 4 * c4; d[0] = v[i].x * gk; d[1] = v[i].y * gk; d[2] = v[i].z * gk; d[3] = v[i].w * gk; }
.LBB0_1578:
	s_waitcnt vmcnt(0)
	v_pk_mul_f32 v[42:43], v[42:43], v[50:51] op_sel_hi:[1,0]
	v_add_u32_e32 v46, 0x410, v95
	ds_write2_b32 v46, v42, v43 offset1:1
	v_pk_mul_f32 v[42:43], v[44:45], v[50:51] op_sel_hi:[1,0]
	v_add_u32_e32 v44, 0x418, v95
	ds_write2_b32 v44, v42, v43 offset1:1
	s_and_b64 vcc, exec, s[0:1]
	v_add_u32_e32 v43, 0x820, v95
	v_add_u32_e32 v44, 0x828, v95
	s_cbranch_vccnz .LBB0_1595
	v_mov_b32_e32 v42, v146
	s_waitcnt vmcnt(0)
	v_pk_mul_f32 v[46:47], v[38:39], v[42:43] op_sel_hi:[1,0]
	ds_write2_b32 v43, v46, v47 offset1:1
	v_pk_mul_f32 v[46:47], v[40:41], v[42:43] op_sel_hi:[1,0]
	v_mov_b32_e32 v42, v147
	ds_write2_b32 v44, v46, v47 offset1:1
	s_cbranch_execnz .LBB0_1581

; #define LAS __attribute__((address_space(3)))
; __device__ __forceinline__ void p0_item(const float* s0, const float* s1, int nv0, int nv1, int N, bf16* dst, int K, LAS float* scr, int lane, const float* gain  ) {
;     ...
;     for (int i = 0; i < 16; ++i) v[i] = ok ? __builtin_nontemporal_load((const f32x4*)(src + (size_t)(4 * i) * N)) : (f32x4){0.f, 0.f, 0.f, 0.f};
; #pragma unroll
;     for (int i = 0; i < 16; ++i) { const float gk = gain ? gain[4 * i + r] : 1.f; LAS float* d = scr + (4 * i + r) * 65 + 4 * c4; d[0] = v[i].x * gk; d[1] = v[i].y * gk; d[2] = v[i].z * gk; d[3] = v[i].w * gk; }
.LBB0_1581:
	s_waitcnt vmcnt(0)
	v_pk_mul_f32 v[34:35], v[34:35], v[42:43] op_sel_hi:[1,0]
	v_add_u32_e32 v38, 0xc30, v95
	ds_write2_b32 v38, v34, v35 offset1:1
	v_pk_mul_f32 v[34:35], v[36:37], v[42:43] op_sel_hi:[1,0]
	v_add_u32_e32 v36, 0xc38, v95
	ds_write2_b32 v36, v34, v35 offset1:1
	s_and_b64 vcc, exec, s[0:1]
	v_add_u32_e32 v35, 0x1040, v95
	v_add_u32_e32 v36, 0x1048, v95
	s_cbranch_vccnz .LBB0_1596
	v_mov_b32_e32 v34, v148
	s_waitcnt vmcnt(0)
	v_pk_mul_f32 v[38:39], v[30:31], v[34:35] op_sel_hi:[1,0]
	ds_write2_b32 v35, v38, v39 offset1:1
	v_pk_mul_f32 v[38:39], v[32:33], v[34:35] op_sel_hi:[1,0]
	v_mov_b32_e32 v34, v149
	ds_write2_b32 v36, v38, v39 offset1:1
	s_cbranch_execnz .LBB0_1584

; #define LAS __attribute__((address_space(3)))
; __device__ __forceinline__ void p0_item(const float* s0, const float* s1, int nv0, int nv1, int N, bf16* dst, int K, LAS float* scr, int lane, const float* gain  ) {
;     ...
;     for (int i = 0; i < 16; ++i) v[i] = ok ? __builtin_nontemporal_load((const f32x4*)(src + (size_t)(4 * i) * N)) : (f32x4){0.f, 0.f, 0.f, 0.f};
; #pragma unroll
;     for (int i = 0; i < 16; ++i) { const float gk = gain ? gain[4 * i + r] : 1.f; LAS float* d = scr + (4 * i + r) * 65 + 4 * c4; d[0] = v[i].x * gk; d[1] = v[i].y * gk; d[2] = v[i].z * gk; d[3] = v[i].w * gk; }
.LBB0_1584:
	s_waitcnt vmcnt(0)
	v_pk_mul_f32 v[26:27], v[26:27], v[34:35] op_sel_hi:[1,0]
	v_add_u32_e32 v30, 0x1450, v95
	ds_write2_b32 v30, v26, v27 offset1:1
	v_pk_mul_f32 v[26:27], v[28:29], v[34:35] op_sel_hi:[1,0]
	v_add_u32_e32 v28, 0x1458, v95
	ds_write2_b32 v28, v26, v27 offset1:1
	s_and_b64 vcc, exec, s[0:1]
	v_add_u32_e32 v27, 0x1860, v95
	v_add_u32_e32 v28, 0x1868, v95
	s_cbranch_vccnz .LBB0_1597
	v_mov_b32_e32 v26, v150
	s_waitcnt vmcnt(0)
	v_pk_mul_f32 v[30:31], v[22:23], v[26:27] op_sel_hi:[1,0]
	ds_write2_b32 v27, v30, v31 offset1:1
	v_pk_mul_f32 v[30:31], v[24:25], v[26:27] op_sel_hi:[1,0]
	v_mov_b32_e32 v26, v151
	ds_write2_b32 v28, v30, v31 offset1:1
	s_cbranch_execnz .LBB0_1587

; #define LAS __attribute__((address_space(3)))
; __device__ __forceinline__ void p0_item(const float* s0, const float* s1, int nv0, int nv1, int N, bf16* dst, int K, LAS float* scr, int lane, const float* gain  ) {
;     ...
;     for (int i = 0; i < 16; ++i) v[i] = ok ? __builtin_nontemporal_load((const f32x4*)(src + (size_t)(4 * i) * N)) : (f32x4){0.f, 0.f, 0.f, 0.f};
; #pragma unroll
;     for (int i = 0; i < 16; ++i) { const float gk = gain ? gain[4 * i + r] : 1.f; LAS float* d = scr + (4 * i + r) * 65 + 4 * c4; d[0] = v[i].x * gk; d[1] = v[i].y * gk; d[2] = v[i].z * gk; d[3] = v[i].w * gk; }
.LBB0_1587:
	s_waitcnt vmcnt(0)
	v_pk_mul_f32 v[18:19], v[18:19], v[26:27] op_sel_hi:[1,0]
	v_add_u32_e32 v22, 0x1c70, v95
	ds_write2_b32 v22, v18, v19 offset1:1
	v_pk_mul_f32 v[18:19], v[20:21], v[26:27] op_sel_hi:[1,0]
	v_add_u32_e32 v20, 0x1c78, v95
	ds_write2_b32 v20, v18, v19 offset1:1
	s_and_b64 vcc, exec, s[0:1]
	v_add_u32_e32 v19, 0x2080, v95
	v_add_u32_e32 v20, 0x2088, v95
	s_cbranch_vccnz .LBB0_1598
	v_mov_b32_e32 v18, v152
	s_waitcnt vmcnt(0)
	v_pk_mul_f32 v[22:23], v[14:15], v[18:19] op_sel_hi:[1,0]
	ds_write2_b32 v19, v22, v23 offset1:1
	v_pk_mul_f32 v[22:23], v[16:17], v[18:19] op_sel_hi:[1,0]
	v_mov_b32_e32 v18, v153
	ds_write2_b32 v20, v22, v23 offset1:1
	s_cbranch_execnz .LBB0_1590

; #define LAS __attribute__((address_space(3)))
; __device__ __forceinline__ void p0_item(const float* s0, const float* s1, int nv0, int nv1, int N, bf16* dst, int K, LAS float* scr, int lane, const float* gain  ) {
;     ...
;     for (int i = 0; i < 16; ++i) v[i] = ok ? __builtin_nontemporal_load((const f32x4*)(src + (size_t)(4 * i) * N)) : (f32x4){0.f, 0.f, 0.f, 0.f};
; #pragma unroll
;     for (int i = 0; i < 16; ++i) { const float gk = gain ? gain[4 * i + r] : 1.f; LAS float* d = scr + (4 * i + r) * 65 + 4 * c4; d[0] = v[i].x * gk; d[1] = v[i].y * gk; d[2] = v[i].z * gk; d[3] = v[i].w * gk; }
.LBB0_1590:
	s_waitcnt vmcnt(0)
	v_pk_mul_f32 v[10:11], v[10:11], v[18:19] op_sel_hi:[1,0]
	v_add_u32_e32 v14, 0x2490, v95
	ds_write2_b32 v14, v10, v11 offset1:1
	v_pk_mul_f32 v[10:11], v[12:13], v[18:19] op_sel_hi:[1,0]
	v_add_u32_e32 v12, 0x2498, v95
	ds_write2_b32 v12, v10, v11 offset1:1
	s_and_b64 vcc, exec, s[0:1]
	v_add_u32_e32 v11, 0x28a0, v95
	v_add_u32_e32 v12, 0x28a8, v95
	s_cbranch_vccnz .LBB0_1599
	v_mov_b32_e32 v10, v154
	s_waitcnt vmcnt(0)
	v_pk_mul_f32 v[14:15], v[6:7], v[10:11] op_sel_hi:[1,0]
	ds_write2_b32 v11, v14, v15 offset1:1
	v_pk_mul_f32 v[14:15], v[8:9], v[10:11] op_sel_hi:[1,0]
	v_mov_b32_e32 v10, v155
	ds_write2_b32 v12, v14, v15 offset1:1
	s_cbranch_execnz .LBB0_1568
	s_branch .LBB0_1600
